# stack + next-phase weight first-K-steps warm-up (one LDS-DMA dword per wave on 16 CUs into a scratch LDS line) after the K-loop of wo/glu/up/down
# speedup vs baseline: 1.1431x; 1.1431x over previous
; #define PG8_STAGE(bufoff, gbase, voff) do { _Pragma("unroll") for (int _i = 0; _i < 2; ++_i) \
;         __builtin_amdgcn_global_load_lds((const unsigned*)((const char*)(gbase) + (voff)[_i]), (LAS unsigned*)(lds + (bufoff) + ldsw + _i * 8192), 16, 0, 0); } while (0)
; #define PG8_LDA(dst, b, h) do { _Pragma("unroll") for (int m = 0; m < 4; ++m) _Pragma("unroll") for (int k = 0; k < 2; ++k) dst[m][k] = *(const LAS bf16x8*)(lds + PG8_SA(b, h) + aoff + m * 2048 + k * 1024); } while (0)
; #define PG8_LDB(dst, b, h) do { _Pragma("unroll") for (int n = 0; n < 2; ++n) _Pragma("unroll") for (int k = 0; k < 2; ++k) dst[n][k] = *(const LAS bf16x8*)(lds + PG8_SB(b, h) + boff + n * 2048 + k * 1024); } while (0)
; #define PG8_MMA(ai, bj, At, Bt) do { __builtin_amdgcn_s_setprio(1); _Pragma("unroll") for (int m = 0; m < 4; ++m) _Pragma("unroll") for (int n = 0; n < 2; ++n) _Pragma("unroll") for (int k = 0; k < 2; ++k) \
;         acc[ai][bj][m][n] = __builtin_amdgcn_mfma_f32_16x16x32_bf16(Bt[n][k], At[m][k], acc[ai][bj][m][n], 0, 0, 0); __builtin_amdgcn_s_setprio(0); } while (0)
; #define PG8_WAIT_V(n) asm volatile("s_waitcnt vmcnt(" #n ")" ::: "memory")
; #define PG8_WAIT_L(n) asm volatile("s_waitcnt lgkmcnt(" #n ")" ::: "memory")
; #define PG8_BAR __builtin_amdgcn_s_barrier()
; #define PG8_SCHED __builtin_amdgcn_sched_barrier(0)
; template <class Epi>
; __device__ __forceinline__ void gemm_phase(LAS unsigned char* lds, const Gemm g, const StaticOrder& S, const Epi& E) {
;     ...
;             const bool last = (t == nt - 2);
;             const char* a1 = cA + (size_t)(t + 1) * kstep;
;             const char* a2 = last ? nA : cA + (size_t)(t + 2) * kstep; const char* b2 = last ? nB : cB + (size_t)(t + 2) * kstep;
;             const char* a3 = a2 + kstep; const char* b3 = b2 + kstep;
;             PG8_LDB(B0, 0, 0); PG8_LDB(B1, 0, 1); PG8_SCHED; PG8_LDA(At, 0, 0); PG8_STAGE(PG8_SA(1, 1), a1 + hstepA, voffA);
;             PG8_WAIT_V(8); PG8_WAIT_L(0); PG8_BAR; PG8_MMA(0, 0, At, B0); PG8_MMA(0, 1, At, B1); PG8_BAR; PG8_SCHED;
;             PG8_LDA(At, 0, 1); PG8_STAGE(PG8_SB(0, 0), b2, voffB); PG8_STAGE(PG8_SB(0, 1), b2 + hstepB, voffB); PG8_STAGE(PG8_SA(0, 0), a2, voffA);
;             PG8_WAIT_V(8); PG8_WAIT_L(0); PG8_BAR; PG8_MMA(1, 0, At, B0); PG8_MMA(1, 1, At, B1); PG8_BAR; PG8_SCHED;
.LBB0_1010:
	s_add_u32 s14, s26, 0xfff80080
	s_addc_u32 s15, s27, -1
	s_add_i32 s41, 0, 0x10000
	s_cmp_eq_u32 s52, 28
	s_cselect_b32 s29, s1, s15
	s_cselect_b32 s28, s3, s14
	s_cselect_b32 s15, s7, s40
	s_cselect_b32 s14, s17, s19
	s_add_i32 s53, 0, 0x14000
	v_add_u32_e32 v142, s41, v1
	v_add_u32_e32 v158, s53, v1
	ds_read_b128 v[130:133], v142
	ds_read_b128 v[134:137], v142 offset:1024
	ds_read_b128 v[138:141], v142 offset:2048
	ds_read_b128 v[142:145], v142 offset:3072
	ds_read_b128 v[146:149], v158
	ds_read_b128 v[150:153], v158 offset:1024
	ds_read_b128 v[154:157], v158 offset:2048
	ds_read_b128 v[158:161], v158 offset:3072
	v_lshl_add_u64 v[178:179], s[26:27], 0, v[196:197]
	s_add_i32 m0, s25, 0xc000
	ds_read_b128 v[162:165], v181
	ds_read_b128 v[166:169], v181 offset:1024
	ds_read_b128 v[170:173], v181 offset:2048
	ds_read_b128 v[174:177], v181 offset:3072
	ds_read_b128 v[200:203], v181 offset:4096
	ds_read_b128 v[204:207], v181 offset:5120
	ds_read_b128 v[208:211], v181 offset:6144
	ds_read_b128 v[212:215], v181 offset:7168
	global_load_lds_dwordx4 v[178:179], off
	v_lshl_add_u64 v[178:179], s[26:27], 0, v[198:199]
	s_add_i32 m0, s25, 0xe000
	s_nop 0
	global_load_lds_dwordx4 v[178:179], off
	s_waitcnt vmcnt(8)
	s_waitcnt lgkmcnt(0)
	s_barrier
	s_setprio 1
	s_waitcnt lgkmcnt(0)
	v_mfma_f32_16x16x32_bf16 v[126:129], v[130:133], v[162:165], v[126:129]
	v_mfma_f32_16x16x32_bf16 v[122:125], v[138:141], v[162:165], v[122:125]
	v_mfma_f32_16x16x32_bf16 v[110:113], v[130:133], v[170:173], v[110:113]
	v_mfma_f32_16x16x32_bf16 v[106:109], v[138:141], v[170:173], v[106:109]
	v_mfma_f32_16x16x32_bf16 v[94:97], v[130:133], v[200:203], v[94:97]
	v_mfma_f32_16x16x32_bf16 v[90:93], v[138:141], v[200:203], v[90:93]
	v_mfma_f32_16x16x32_bf16 v[82:85], v[130:133], v[208:211], v[82:85]
	v_mfma_f32_16x16x32_bf16 v[74:77], v[138:141], v[208:211], v[74:77]
	v_mfma_f32_16x16x32_bf16 v[126:129], v[134:137], v[166:169], v[126:129]
	v_mfma_f32_16x16x32_bf16 v[122:125], v[142:145], v[166:169], v[122:125]
	v_mfma_f32_16x16x32_bf16 v[110:113], v[134:137], v[174:177], v[110:113]
	v_mfma_f32_16x16x32_bf16 v[106:109], v[142:145], v[174:177], v[106:109]
	v_mfma_f32_16x16x32_bf16 v[94:97], v[134:137], v[204:207], v[94:97]
	v_mfma_f32_16x16x32_bf16 v[90:93], v[142:145], v[204:207], v[90:93]
	v_mfma_f32_16x16x32_bf16 v[82:85], v[134:137], v[212:215], v[82:85]
	v_mfma_f32_16x16x32_bf16 v[74:77], v[142:145], v[212:215], v[74:77]
	s_setprio 0
	s_setprio 1
	v_mfma_f32_16x16x32_bf16 v[118:121], v[146:149], v[162:165], v[118:121]
	v_mfma_f32_16x16x32_bf16 v[114:117], v[154:157], v[162:165], v[114:117]
	v_mfma_f32_16x16x32_bf16 v[102:105], v[146:149], v[170:173], v[102:105]
	v_mfma_f32_16x16x32_bf16 v[98:101], v[154:157], v[170:173], v[98:101]
	v_mfma_f32_16x16x32_bf16 v[86:89], v[146:149], v[200:203], v[86:89]
	v_mfma_f32_16x16x32_bf16 v[78:81], v[154:157], v[200:203], v[78:81]
	v_mfma_f32_16x16x32_bf16 v[70:73], v[146:149], v[208:211], v[70:73]
	v_mfma_f32_16x16x32_bf16 v[66:69], v[154:157], v[208:211], v[66:69]
	v_mfma_f32_16x16x32_bf16 v[118:121], v[150:153], v[166:169], v[118:121]
	v_mfma_f32_16x16x32_bf16 v[114:117], v[158:161], v[166:169], v[114:117]
	v_mfma_f32_16x16x32_bf16 v[102:105], v[150:153], v[174:177], v[102:105]
	v_mfma_f32_16x16x32_bf16 v[98:101], v[158:161], v[174:177], v[98:101]
	v_mfma_f32_16x16x32_bf16 v[86:89], v[150:153], v[204:207], v[86:89]
	v_mfma_f32_16x16x32_bf16 v[78:81], v[158:161], v[204:207], v[78:81]
	v_mfma_f32_16x16x32_bf16 v[70:73], v[150:153], v[212:215], v[70:73]
	v_mfma_f32_16x16x32_bf16 v[66:69], v[158:161], v[212:215], v[66:69]
	s_setprio 0
	s_barrier
	s_add_i32 s41, s41, s30
	v_lshl_add_u64 v[178:179], s[14:15], 0, v[190:191]
	s_mov_b32 m0, s41
	ds_read_b128 v[162:165], v181 offset:16384
	ds_read_b128 v[166:169], v181 offset:17408
	ds_read_b128 v[170:173], v181 offset:18432
	ds_read_b128 v[174:177], v181 offset:19456
	ds_read_b128 v[200:203], v181 offset:20480
	ds_read_b128 v[204:207], v181 offset:21504
	ds_read_b128 v[208:211], v181 offset:22528
	ds_read_b128 v[212:215], v181 offset:23552
	global_load_lds_dwordx4 v[178:179], off
	s_add_i32 m0, s41, 0x2000
	s_add_u32 s62, s14, 0x80000
	v_lshl_add_u64 v[184:185], s[14:15], 0, v[194:195]
	s_addc_u32 s63, s15, 0
	s_add_i32 s41, s53, s30
	global_load_lds_dwordx4 v[184:185], off
	v_lshl_add_u64 v[216:217], s[62:63], 0, v[190:191]
	s_mov_b32 m0, s41
	v_lshl_add_u64 v[218:219], s[28:29], 0, v[192:193]
	global_load_lds_dwordx4 v[216:217], off
	v_lshl_add_u64 v[216:217], s[62:63], 0, v[194:195]
	s_add_i32 m0, s41, 0x2000
	s_nop 0
	global_load_lds_dwordx4 v[216:217], off
	v_lshl_add_u64 v[216:217], s[28:29], 0, v[188:189]
	s_mov_b32 m0, s25
	s_nop 0
	global_load_lds_dwordx4 v[216:217], off
	s_mov_b32 m0, s31
	s_nop 0
	global_load_lds_dwordx4 v[218:219], off
	s_waitcnt vmcnt(8)
	s_waitcnt lgkmcnt(0)
	s_barrier
; #define PG8_STAGE(bufoff, gbase, voff) do { _Pragma("unroll") for (int _i = 0; _i < 2; ++_i) \
;         __builtin_amdgcn_global_load_lds((const unsigned*)((const char*)(gbase) + (voff)[_i]), (LAS unsigned*)(lds + (bufoff) + ldsw + _i * 8192), 16, 0, 0); } while (0)
; #define PG8_LDA(dst, b, h) do { _Pragma("unroll") for (int m = 0; m < 4; ++m) _Pragma("unroll") for (int k = 0; k < 2; ++k) dst[m][k] = *(const LAS bf16x8*)(lds + PG8_SA(b, h) + aoff + m * 2048 + k * 1024); } while (0)
; #define PG8_LDB(dst, b, h) do { _Pragma("unroll") for (int n = 0; n < 2; ++n) _Pragma("unroll") for (int k = 0; k < 2; ++k) dst[n][k] = *(const LAS bf16x8*)(lds + PG8_SB(b, h) + boff + n * 2048 + k * 1024); } while (0)
; #define PG8_MMA(ai, bj, At, Bt) do { __builtin_amdgcn_s_setprio(1); _Pragma("unroll") for (int m = 0; m < 4; ++m) _Pragma("unroll") for (int n = 0; n < 2; ++n) _Pragma("unroll") for (int k = 0; k < 2; ++k) \
;         acc[ai][bj][m][n] = __builtin_amdgcn_mfma_f32_16x16x32_bf16(Bt[n][k], At[m][k], acc[ai][bj][m][n], 0, 0, 0); __builtin_amdgcn_s_setprio(0); } while (0)
; #define PG8_WAIT_V(n) asm volatile("s_waitcnt vmcnt(" #n ")" ::: "memory")
; #define PG8_WAIT_L(n) asm volatile("s_waitcnt lgkmcnt(" #n ")" ::: "memory")
; #define PG8_BAR __builtin_amdgcn_s_barrier()
; #define PG8_SCHED __builtin_amdgcn_sched_barrier(0)
; template <class Epi>
; __device__ __forceinline__ void gemm_phase(LAS unsigned char* lds, const Gemm g, const StaticOrder& S, const Epi& E) {
;     ...
;             PG8_WAIT_V(8); PG8_WAIT_L(0); PG8_BAR; PG8_MMA(1, 0, At, B0); PG8_MMA(1, 1, At, B1); PG8_BAR; PG8_SCHED;
;             PG8_LDB(B0, 1, 0); PG8_LDB(B1, 1, 1); PG8_SCHED; PG8_LDA(At, 1, 0); PG8_STAGE(PG8_SA(0, 1), a2 + hstepA, voffA);
;             PG8_WAIT_V(8); PG8_WAIT_L(0); PG8_BAR; PG8_MMA(0, 0, At, B0); PG8_MMA(0, 1, At, B1); PG8_BAR; PG8_SCHED;
;             PG8_LDA(At, 1, 1); PG8_STAGE(PG8_SB(1, 0), b3, voffB); PG8_STAGE(PG8_SB(1, 1), b3 + hstepB, voffB); PG8_STAGE(PG8_SA(1, 0), a3, voffA);
;             PG8_WAIT_V(8); PG8_WAIT_L(0); PG8_BAR; PG8_MMA(1, 0, At, B0); PG8_MMA(1, 1, At, B1); PG8_BAR; PG8_SCHED;
	s_setprio 1
	s_waitcnt lgkmcnt(0)
	v_mfma_f32_16x16x32_bf16 v[62:65], v[130:133], v[162:165], v[62:65]
	v_mfma_f32_16x16x32_bf16 v[58:61], v[138:141], v[162:165], v[58:61]
	v_mfma_f32_16x16x32_bf16 v[50:53], v[130:133], v[170:173], v[50:53]
	v_mfma_f32_16x16x32_bf16 v[42:45], v[138:141], v[170:173], v[42:45]
	v_mfma_f32_16x16x32_bf16 v[30:33], v[130:133], v[200:203], v[30:33]
	v_mfma_f32_16x16x32_bf16 v[26:29], v[138:141], v[200:203], v[26:29]
	v_mfma_f32_16x16x32_bf16 v[18:21], v[130:133], v[208:211], v[18:21]
	v_mfma_f32_16x16x32_bf16 v[10:13], v[138:141], v[208:211], v[10:13]
	v_mfma_f32_16x16x32_bf16 v[62:65], v[134:137], v[166:169], v[62:65]
	v_mfma_f32_16x16x32_bf16 v[58:61], v[142:145], v[166:169], v[58:61]
	v_mfma_f32_16x16x32_bf16 v[50:53], v[134:137], v[174:177], v[50:53]
	v_mfma_f32_16x16x32_bf16 v[42:45], v[142:145], v[174:177], v[42:45]
	v_mfma_f32_16x16x32_bf16 v[30:33], v[134:137], v[204:207], v[30:33]
	v_mfma_f32_16x16x32_bf16 v[26:29], v[142:145], v[204:207], v[26:29]
	v_mfma_f32_16x16x32_bf16 v[18:21], v[134:137], v[212:215], v[18:21]
	v_mfma_f32_16x16x32_bf16 v[10:13], v[142:145], v[212:215], v[10:13]
	s_setprio 0
	s_setprio 1
	v_mfma_f32_16x16x32_bf16 v[54:57], v[146:149], v[162:165], v[54:57]
	v_mfma_f32_16x16x32_bf16 v[46:49], v[154:157], v[162:165], v[46:49]
	v_mfma_f32_16x16x32_bf16 v[38:41], v[146:149], v[170:173], v[38:41]
	v_mfma_f32_16x16x32_bf16 v[34:37], v[154:157], v[170:173], v[34:37]
	v_mfma_f32_16x16x32_bf16 v[22:25], v[146:149], v[200:203], v[22:25]
	v_mfma_f32_16x16x32_bf16 v[14:17], v[154:157], v[200:203], v[14:17]
	v_mfma_f32_16x16x32_bf16 v[6:9], v[146:149], v[208:211], v[6:9]
	v_mfma_f32_16x16x32_bf16 v[2:5], v[154:157], v[208:211], v[2:5]
	v_mfma_f32_16x16x32_bf16 v[54:57], v[150:153], v[166:169], v[54:57]
	v_mfma_f32_16x16x32_bf16 v[46:49], v[158:161], v[166:169], v[46:49]
	v_mfma_f32_16x16x32_bf16 v[38:41], v[150:153], v[174:177], v[38:41]
	v_mfma_f32_16x16x32_bf16 v[34:37], v[158:161], v[174:177], v[34:37]
	v_mfma_f32_16x16x32_bf16 v[22:25], v[150:153], v[204:207], v[22:25]
	v_mfma_f32_16x16x32_bf16 v[14:17], v[158:161], v[204:207], v[14:17]
	v_mfma_f32_16x16x32_bf16 v[6:9], v[150:153], v[212:215], v[6:9]
	v_mfma_f32_16x16x32_bf16 v[2:5], v[158:161], v[212:215], v[2:5]
	s_setprio 0
	s_barrier
	s_add_i32 s41, 0, 0x18000
	s_add_i32 s53, 0, 0x1c000
	v_add_u32_e32 v142, s41, v1
	v_add_u32_e32 v158, s53, v1
	ds_read_b128 v[130:133], v142
	ds_read_b128 v[134:137], v142 offset:1024
	ds_read_b128 v[138:141], v142 offset:2048
	ds_read_b128 v[142:145], v142 offset:3072
	ds_read_b128 v[146:149], v158
	ds_read_b128 v[150:153], v158 offset:1024
	ds_read_b128 v[154:157], v158 offset:2048
	ds_read_b128 v[158:161], v158 offset:3072
	s_add_u32 s28, s28, 0x80000
	s_addc_u32 s29, s29, 0
	s_mov_b32 m0, s33
	v_lshl_add_u64 v[220:221], s[28:29], 0, v[188:189]
	ds_read_b128 v[162:165], v181 offset:32768
	ds_read_b128 v[166:169], v181 offset:33792
	ds_read_b128 v[170:173], v181 offset:34816
	ds_read_b128 v[174:177], v181 offset:35840
	ds_read_b128 v[200:203], v181 offset:36864
	ds_read_b128 v[204:207], v181 offset:37888
	ds_read_b128 v[208:211], v181 offset:38912
	ds_read_b128 v[212:215], v181 offset:39936
	global_load_lds_dwordx4 v[220:221], off
	v_lshl_add_u64 v[220:221], s[28:29], 0, v[192:193]
	s_mov_b32 m0, s34
	s_nop 0
	global_load_lds_dwordx4 v[220:221], off
	s_waitcnt vmcnt(8)
	s_waitcnt lgkmcnt(0)
	s_barrier
	s_setprio 1
	s_waitcnt lgkmcnt(0)
	v_mfma_f32_16x16x32_bf16 v[126:129], v[130:133], v[162:165], v[126:129]
	v_mfma_f32_16x16x32_bf16 v[122:125], v[138:141], v[162:165], v[122:125]
	v_mfma_f32_16x16x32_bf16 v[110:113], v[130:133], v[170:173], v[110:113]
	v_mfma_f32_16x16x32_bf16 v[106:109], v[138:141], v[170:173], v[106:109]
	v_mfma_f32_16x16x32_bf16 v[94:97], v[130:133], v[200:203], v[94:97]
	v_mfma_f32_16x16x32_bf16 v[90:93], v[138:141], v[200:203], v[90:93]
	v_mfma_f32_16x16x32_bf16 v[82:85], v[130:133], v[208:211], v[82:85]
	v_mfma_f32_16x16x32_bf16 v[74:77], v[138:141], v[208:211], v[74:77]
	v_mfma_f32_16x16x32_bf16 v[126:129], v[134:137], v[166:169], v[126:129]
	v_mfma_f32_16x16x32_bf16 v[122:125], v[142:145], v[166:169], v[122:125]
	v_mfma_f32_16x16x32_bf16 v[110:113], v[134:137], v[174:177], v[110:113]
	v_mfma_f32_16x16x32_bf16 v[106:109], v[142:145], v[174:177], v[106:109]
	v_mfma_f32_16x16x32_bf16 v[94:97], v[134:137], v[204:207], v[94:97]
	v_mfma_f32_16x16x32_bf16 v[90:93], v[142:145], v[204:207], v[90:93]
	v_mfma_f32_16x16x32_bf16 v[82:85], v[134:137], v[212:215], v[82:85]
	v_mfma_f32_16x16x32_bf16 v[74:77], v[142:145], v[212:215], v[74:77]
	s_setprio 0
	s_setprio 1
	v_mfma_f32_16x16x32_bf16 v[118:121], v[146:149], v[162:165], v[118:121]
	v_mfma_f32_16x16x32_bf16 v[114:117], v[154:157], v[162:165], v[114:117]
	v_mfma_f32_16x16x32_bf16 v[102:105], v[146:149], v[170:173], v[102:105]
	v_mfma_f32_16x16x32_bf16 v[98:101], v[154:157], v[170:173], v[98:101]
	v_mfma_f32_16x16x32_bf16 v[86:89], v[146:149], v[200:203], v[86:89]
	v_mfma_f32_16x16x32_bf16 v[78:81], v[154:157], v[200:203], v[78:81]
	v_mfma_f32_16x16x32_bf16 v[70:73], v[146:149], v[208:211], v[70:73]
	v_mfma_f32_16x16x32_bf16 v[66:69], v[154:157], v[208:211], v[66:69]
	v_mfma_f32_16x16x32_bf16 v[118:121], v[150:153], v[166:169], v[118:121]
	v_mfma_f32_16x16x32_bf16 v[114:117], v[158:161], v[166:169], v[114:117]
	v_mfma_f32_16x16x32_bf16 v[102:105], v[150:153], v[174:177], v[102:105]
	v_mfma_f32_16x16x32_bf16 v[98:101], v[158:161], v[174:177], v[98:101]
	v_mfma_f32_16x16x32_bf16 v[86:89], v[150:153], v[204:207], v[86:89]
	v_mfma_f32_16x16x32_bf16 v[78:81], v[158:161], v[204:207], v[78:81]
	v_mfma_f32_16x16x32_bf16 v[70:73], v[150:153], v[212:215], v[70:73]
	v_mfma_f32_16x16x32_bf16 v[66:69], v[158:161], v[212:215], v[66:69]
	s_setprio 0
	s_barrier
; #define PG8_STAGE(bufoff, gbase, voff) do { _Pragma("unroll") for (int _i = 0; _i < 2; ++_i) \
;         __builtin_amdgcn_global_load_lds((const unsigned*)((const char*)(gbase) + (voff)[_i]), (LAS unsigned*)(lds + (bufoff) + ldsw + _i * 8192), 16, 0, 0); } while (0)
; #define PG8_LDA(dst, b, h) do { _Pragma("unroll") for (int m = 0; m < 4; ++m) _Pragma("unroll") for (int k = 0; k < 2; ++k) dst[m][k] = *(const LAS bf16x8*)(lds + PG8_SA(b, h) + aoff + m * 2048 + k * 1024); } while (0)
; #define PG8_MMA(ai, bj, At, Bt) do { __builtin_amdgcn_s_setprio(1); _Pragma("unroll") for (int m = 0; m < 4; ++m) _Pragma("unroll") for (int n = 0; n < 2; ++n) _Pragma("unroll") for (int k = 0; k < 2; ++k) \
;         acc[ai][bj][m][n] = __builtin_amdgcn_mfma_f32_16x16x32_bf16(Bt[n][k], At[m][k], acc[ai][bj][m][n], 0, 0, 0); __builtin_amdgcn_s_setprio(0); } while (0)
; #define PG8_WAIT_V(n) asm volatile("s_waitcnt vmcnt(" #n ")" ::: "memory")
; #define PG8_WAIT_L(n) asm volatile("s_waitcnt lgkmcnt(" #n ")" ::: "memory")
; #define PG8_BAR __builtin_amdgcn_s_barrier()
; #define PG8_SCHED __builtin_amdgcn_sched_barrier(0)
; template <class Epi>
; __device__ __forceinline__ void gemm_phase(LAS unsigned char* lds, const Gemm g, const StaticOrder& S, const Epi& E) {
;     ...
;             PG8_LDA(At, 1, 1); PG8_STAGE(PG8_SB(1, 0), b3, voffB); PG8_STAGE(PG8_SB(1, 1), b3 + hstepB, voffB); PG8_STAGE(PG8_SA(1, 0), a3, voffA);
;             PG8_WAIT_V(8); PG8_WAIT_L(0); PG8_BAR; PG8_MMA(1, 0, At, B0); PG8_MMA(1, 1, At, B1); PG8_BAR; PG8_SCHED;
;         }
;         if (wr == 0) PG8_BAR;
	s_add_i32 s28, s41, s30
	v_lshl_add_u64 v[178:179], v[178:179], 0, s[84:85]
	s_mov_b32 m0, s28
	ds_read_b128 v[162:165], v181 offset:49152
	ds_read_b128 v[166:169], v181 offset:50176
	ds_read_b128 v[170:173], v181 offset:51200
	ds_read_b128 v[174:177], v181 offset:52224
	ds_read_b128 v[200:203], v181 offset:53248
	ds_read_b128 v[204:207], v181 offset:54272
	ds_read_b128 v[208:211], v181 offset:55296
	ds_read_b128 v[212:215], v181 offset:56320
	global_load_lds_dwordx4 v[178:179], off
	s_add_i32 m0, s28, 0x2000
	s_add_u32 s14, s14, 0x80080
	v_lshl_add_u64 v[178:179], v[184:185], 0, s[84:85]
	s_addc_u32 s15, s15, 0
	s_add_i32 s28, s53, s30
	global_load_lds_dwordx4 v[178:179], off
	v_lshl_add_u64 v[178:179], s[14:15], 0, v[190:191]
	s_mov_b32 m0, s28
	s_nop 0
	global_load_lds_dwordx4 v[178:179], off
	v_lshl_add_u64 v[178:179], s[14:15], 0, v[194:195]
	s_add_i32 m0, s28, 0x2000
	s_nop 0
	global_load_lds_dwordx4 v[178:179], off
	v_lshl_add_u64 v[178:179], v[216:217], 0, s[84:85]
	s_mov_b32 m0, s44
	s_nop 0
	global_load_lds_dwordx4 v[178:179], off
	v_lshl_add_u64 v[178:179], v[218:219], 0, s[84:85]
	s_mov_b32 m0, s45
	s_nop 0
	global_load_lds_dwordx4 v[178:179], off
	s_waitcnt vmcnt(8)
	s_waitcnt lgkmcnt(0)
	s_barrier
	s_setprio 1
	s_waitcnt lgkmcnt(0)
	v_mfma_f32_16x16x32_bf16 v[62:65], v[130:133], v[162:165], v[62:65]
	v_mfma_f32_16x16x32_bf16 v[58:61], v[138:141], v[162:165], v[58:61]
	v_mfma_f32_16x16x32_bf16 v[50:53], v[130:133], v[170:173], v[50:53]
	v_mfma_f32_16x16x32_bf16 v[42:45], v[138:141], v[170:173], v[42:45]
	v_mfma_f32_16x16x32_bf16 v[30:33], v[130:133], v[200:203], v[30:33]
	v_mfma_f32_16x16x32_bf16 v[26:29], v[138:141], v[200:203], v[26:29]
	v_mfma_f32_16x16x32_bf16 v[18:21], v[130:133], v[208:211], v[18:21]
	v_mfma_f32_16x16x32_bf16 v[10:13], v[138:141], v[208:211], v[10:13]
	v_mfma_f32_16x16x32_bf16 v[62:65], v[134:137], v[166:169], v[62:65]
	v_mfma_f32_16x16x32_bf16 v[58:61], v[142:145], v[166:169], v[58:61]
	v_mfma_f32_16x16x32_bf16 v[50:53], v[134:137], v[174:177], v[50:53]
	v_mfma_f32_16x16x32_bf16 v[42:45], v[142:145], v[174:177], v[42:45]
	v_mfma_f32_16x16x32_bf16 v[30:33], v[134:137], v[204:207], v[30:33]
	v_mfma_f32_16x16x32_bf16 v[26:29], v[142:145], v[204:207], v[26:29]
	v_mfma_f32_16x16x32_bf16 v[18:21], v[134:137], v[212:215], v[18:21]
	v_mfma_f32_16x16x32_bf16 v[10:13], v[142:145], v[212:215], v[10:13]
	s_setprio 0
	s_setprio 1
	v_mfma_f32_16x16x32_bf16 v[54:57], v[146:149], v[162:165], v[54:57]
	v_mfma_f32_16x16x32_bf16 v[46:49], v[154:157], v[162:165], v[46:49]
	v_mfma_f32_16x16x32_bf16 v[38:41], v[146:149], v[170:173], v[38:41]
	v_mfma_f32_16x16x32_bf16 v[34:37], v[154:157], v[170:173], v[34:37]
	v_mfma_f32_16x16x32_bf16 v[22:25], v[146:149], v[200:203], v[22:25]
	v_mfma_f32_16x16x32_bf16 v[14:17], v[154:157], v[200:203], v[14:17]
	v_mfma_f32_16x16x32_bf16 v[6:9], v[146:149], v[208:211], v[6:9]
	v_mfma_f32_16x16x32_bf16 v[2:5], v[154:157], v[208:211], v[2:5]
	v_mfma_f32_16x16x32_bf16 v[54:57], v[150:153], v[166:169], v[54:57]
	v_mfma_f32_16x16x32_bf16 v[46:49], v[158:161], v[166:169], v[46:49]
	v_mfma_f32_16x16x32_bf16 v[38:41], v[150:153], v[174:177], v[38:41]
	v_mfma_f32_16x16x32_bf16 v[34:37], v[158:161], v[174:177], v[34:37]
	v_mfma_f32_16x16x32_bf16 v[22:25], v[150:153], v[204:207], v[22:25]
	v_mfma_f32_16x16x32_bf16 v[14:17], v[158:161], v[204:207], v[14:17]
	v_mfma_f32_16x16x32_bf16 v[6:9], v[150:153], v[212:215], v[6:9]
	v_mfma_f32_16x16x32_bf16 v[2:5], v[158:161], v[212:215], v[2:5]
	s_setprio 0
	s_barrier
	s_add_i32 s52, s52, 2
	s_add_u32 s26, s26, 0x100
	s_addc_u32 s27, s27, 0
	s_add_u32 s19, s19, 0x100
	s_addc_u32 s40, s40, 0
	s_cmp_gt_u32 s52, 29
	s_cbranch_scc0 .LBB0_1010
	s_cmp_ge_u32 s74, 16
	s_cbranch_scc1 .Lwpf_a
	s_lshl_b32 s100, s74, 9
	v_add_u32_e32 v130, s100, v246
	v_lshrrev_b32_e32 v131, 2, v130
	v_and_b32_e32 v130, 3, v130
	v_lshlrev_b32_e32 v130, 7, v130
	v_lshl_add_u32 v130, v131, 12, v130
	s_add_u32 s100, s88, 0x1800000
	s_addc_u32 s101, s89, 0
	s_mov_b32 m0, 0x21000
	s_nop 0
	global_load_lds_dword v130, s[100:101]
.Lwpf_a:
	s_and_b64 vcc, exec, s[12:13]
	s_cbranch_vccz .LBB0_1013
	s_barrier

; #define PG8_STAGE(bufoff, gbase, voff) do { _Pragma("unroll") for (int _i = 0; _i < 2; ++_i) \
;         __builtin_amdgcn_global_load_lds((const unsigned*)((const char*)(gbase) + (voff)[_i]), (LAS unsigned*)(lds + (bufoff) + ldsw + _i * 8192), 16, 0, 0); } while (0)
; #define PG8_LDA(dst, b, h) do { _Pragma("unroll") for (int m = 0; m < 4; ++m) _Pragma("unroll") for (int k = 0; k < 2; ++k) dst[m][k] = *(const LAS bf16x8*)(lds + PG8_SA(b, h) + aoff + m * 2048 + k * 1024); } while (0)
; #define PG8_LDB(dst, b, h) do { _Pragma("unroll") for (int n = 0; n < 2; ++n) _Pragma("unroll") for (int k = 0; k < 2; ++k) dst[n][k] = *(const LAS bf16x8*)(lds + PG8_SB(b, h) + boff + n * 2048 + k * 1024); } while (0)
; #define PG8_MMA(ai, bj, At, Bt) do { __builtin_amdgcn_s_setprio(1); _Pragma("unroll") for (int m = 0; m < 4; ++m) _Pragma("unroll") for (int n = 0; n < 2; ++n) _Pragma("unroll") for (int k = 0; k < 2; ++k) \
;         acc[ai][bj][m][n] = __builtin_amdgcn_mfma_f32_16x16x32_bf16(Bt[n][k], At[m][k], acc[ai][bj][m][n], 0, 0, 0); __builtin_amdgcn_s_setprio(0); } while (0)
; #define PG8_WAIT_V(n) asm volatile("s_waitcnt vmcnt(" #n ")" ::: "memory")
; #define PG8_WAIT_L(n) asm volatile("s_waitcnt lgkmcnt(" #n ")" ::: "memory")
; #define PG8_BAR __builtin_amdgcn_s_barrier()
; #define PG8_SCHED __builtin_amdgcn_sched_barrier(0)
; template <class Epi>
; __device__ __forceinline__ void gemm_phase(LAS unsigned char* lds, const Gemm g, const StaticOrder& S, const Epi& E) {
;     ...
;             const bool last = (t == nt - 2);
;             const char* a1 = cA + (size_t)(t + 1) * kstep;
;             const char* a2 = last ? nA : cA + (size_t)(t + 2) * kstep; const char* b2 = last ? nB : cB + (size_t)(t + 2) * kstep;
;             const char* a3 = a2 + kstep; const char* b3 = b2 + kstep;
;             PG8_LDB(B0, 0, 0); PG8_LDB(B1, 0, 1); PG8_SCHED; PG8_LDA(At, 0, 0); PG8_STAGE(PG8_SA(1, 1), a1 + hstepA, voffA);
;             PG8_WAIT_V(8); PG8_WAIT_L(0); PG8_BAR; PG8_MMA(0, 0, At, B0); PG8_MMA(0, 1, At, B1); PG8_BAR; PG8_SCHED;
;             PG8_LDA(At, 0, 1); PG8_STAGE(PG8_SB(0, 0), b2, voffB); PG8_STAGE(PG8_SB(0, 1), b2 + hstepB, voffB); PG8_STAGE(PG8_SA(0, 0), a2, voffA);
;             PG8_WAIT_V(8); PG8_WAIT_L(0); PG8_BAR; PG8_MMA(1, 0, At, B0); PG8_MMA(1, 1, At, B1); PG8_BAR; PG8_SCHED;
.LBB0_1324:
	s_add_u32 s14, s24, 0xfff80080
	s_addc_u32 s15, s25, -1
	s_add_i32 s53, 0, 0x10000
	s_cmp_eq_u32 s41, 28
	s_cselect_b32 s27, s3, s15
	s_cselect_b32 s26, s7, s14
	s_cselect_b32 s15, s13, s52
	s_cselect_b32 s14, s17, s40
	s_add_i32 s69, 0, 0x14000
	v_add_u32_e32 v142, s53, v1
	v_add_u32_e32 v158, s69, v1
	ds_read_b128 v[130:133], v142
	ds_read_b128 v[134:137], v142 offset:1024
	ds_read_b128 v[138:141], v142 offset:2048
	ds_read_b128 v[142:145], v142 offset:3072
	ds_read_b128 v[146:149], v158
	ds_read_b128 v[150:153], v158 offset:1024
	ds_read_b128 v[154:157], v158 offset:2048
	ds_read_b128 v[158:161], v158 offset:3072
	v_lshl_add_u64 v[178:179], s[24:25], 0, v[170:171]
	s_add_i32 m0, s23, 0xc000
	ds_read_b128 v[162:165], v181
	ds_read_b128 v[174:177], v181 offset:1024
	ds_read_b128 v[188:191], v181 offset:2048
	ds_read_b128 v[192:195], v181 offset:3072
	ds_read_b128 v[196:199], v181 offset:4096
	ds_read_b128 v[200:203], v181 offset:5120
	ds_read_b128 v[204:207], v181 offset:6144
	ds_read_b128 v[208:211], v181 offset:7168
	global_load_lds_dwordx4 v[178:179], off
	v_lshl_add_u64 v[178:179], s[24:25], 0, v[172:173]
	s_add_i32 m0, s23, 0xe000
	s_nop 0
	global_load_lds_dwordx4 v[178:179], off
	s_waitcnt vmcnt(8)
	s_waitcnt lgkmcnt(0)
	s_barrier
	s_setprio 1
	s_waitcnt lgkmcnt(0)
	v_mfma_f32_16x16x32_bf16 v[122:125], v[130:133], v[162:165], v[122:125]
	v_mfma_f32_16x16x32_bf16 v[118:121], v[138:141], v[162:165], v[118:121]
	v_mfma_f32_16x16x32_bf16 v[110:113], v[130:133], v[188:191], v[110:113]
	v_mfma_f32_16x16x32_bf16 v[102:105], v[138:141], v[188:191], v[102:105]
	v_mfma_f32_16x16x32_bf16 v[94:97], v[130:133], v[196:199], v[94:97]
	v_mfma_f32_16x16x32_bf16 v[86:89], v[138:141], v[196:199], v[86:89]
	v_mfma_f32_16x16x32_bf16 v[78:81], v[130:133], v[204:207], v[78:81]
	v_mfma_f32_16x16x32_bf16 v[70:73], v[138:141], v[204:207], v[70:73]
	v_mfma_f32_16x16x32_bf16 v[122:125], v[134:137], v[174:177], v[122:125]
	v_mfma_f32_16x16x32_bf16 v[118:121], v[142:145], v[174:177], v[118:121]
	v_mfma_f32_16x16x32_bf16 v[110:113], v[134:137], v[192:195], v[110:113]
	v_mfma_f32_16x16x32_bf16 v[102:105], v[142:145], v[192:195], v[102:105]
	v_mfma_f32_16x16x32_bf16 v[94:97], v[134:137], v[200:203], v[94:97]
	v_mfma_f32_16x16x32_bf16 v[86:89], v[142:145], v[200:203], v[86:89]
	v_mfma_f32_16x16x32_bf16 v[78:81], v[134:137], v[208:211], v[78:81]
	v_mfma_f32_16x16x32_bf16 v[70:73], v[142:145], v[208:211], v[70:73]
	s_setprio 0
	s_setprio 1
	v_mfma_f32_16x16x32_bf16 v[126:129], v[146:149], v[162:165], v[126:129]
	v_mfma_f32_16x16x32_bf16 v[114:117], v[154:157], v[162:165], v[114:117]
	v_mfma_f32_16x16x32_bf16 v[106:109], v[146:149], v[188:191], v[106:109]
	v_mfma_f32_16x16x32_bf16 v[98:101], v[154:157], v[188:191], v[98:101]
	v_mfma_f32_16x16x32_bf16 v[90:93], v[146:149], v[196:199], v[90:93]
	v_mfma_f32_16x16x32_bf16 v[82:85], v[154:157], v[196:199], v[82:85]
	v_mfma_f32_16x16x32_bf16 v[74:77], v[146:149], v[204:207], v[74:77]
	v_mfma_f32_16x16x32_bf16 v[66:69], v[154:157], v[204:207], v[66:69]
	v_mfma_f32_16x16x32_bf16 v[126:129], v[150:153], v[174:177], v[126:129]
	v_mfma_f32_16x16x32_bf16 v[114:117], v[158:161], v[174:177], v[114:117]
	v_mfma_f32_16x16x32_bf16 v[106:109], v[150:153], v[192:195], v[106:109]
	v_mfma_f32_16x16x32_bf16 v[98:101], v[158:161], v[192:195], v[98:101]
	v_mfma_f32_16x16x32_bf16 v[90:93], v[150:153], v[200:203], v[90:93]
	v_mfma_f32_16x16x32_bf16 v[82:85], v[158:161], v[200:203], v[82:85]
	v_mfma_f32_16x16x32_bf16 v[74:77], v[150:153], v[208:211], v[74:77]
	v_mfma_f32_16x16x32_bf16 v[66:69], v[158:161], v[208:211], v[66:69]
	s_setprio 0
	s_barrier
	s_add_i32 s53, s53, s28
	v_lshl_add_u64 v[178:179], s[14:15], 0, v[166:167]
	s_mov_b32 m0, s53
	ds_read_b128 v[162:165], v181 offset:16384
	ds_read_b128 v[174:177], v181 offset:17408
	ds_read_b128 v[188:191], v181 offset:18432
	ds_read_b128 v[192:195], v181 offset:19456
	ds_read_b128 v[196:199], v181 offset:20480
	ds_read_b128 v[200:203], v181 offset:21504
	ds_read_b128 v[204:207], v181 offset:22528
	ds_read_b128 v[208:211], v181 offset:23552
	global_load_lds_dwordx4 v[178:179], off
	s_add_i32 m0, s53, 0x2000
	s_add_u32 s64, s14, 0x80000
	v_lshl_add_u64 v[184:185], s[14:15], 0, v[168:169]
	s_addc_u32 s65, s15, 0
	s_add_i32 s53, s69, s28
	global_load_lds_dwordx4 v[184:185], off
	v_lshl_add_u64 v[212:213], s[64:65], 0, v[166:167]
	s_mov_b32 m0, s53
	v_lshl_add_u64 v[214:215], s[26:27], 0, v[168:169]
	global_load_lds_dwordx4 v[212:213], off
	v_lshl_add_u64 v[212:213], s[64:65], 0, v[168:169]
	s_add_i32 m0, s53, 0x2000
	s_nop 0
	global_load_lds_dwordx4 v[212:213], off
	v_lshl_add_u64 v[212:213], s[26:27], 0, v[166:167]
	s_mov_b32 m0, s23
	s_nop 0
	global_load_lds_dwordx4 v[212:213], off
	s_mov_b32 m0, s29
	s_nop 0
	global_load_lds_dwordx4 v[214:215], off
	s_waitcnt vmcnt(8)
	s_waitcnt lgkmcnt(0)
	s_barrier
; #define PG8_STAGE(bufoff, gbase, voff) do { _Pragma("unroll") for (int _i = 0; _i < 2; ++_i) \
;         __builtin_amdgcn_global_load_lds((const unsigned*)((const char*)(gbase) + (voff)[_i]), (LAS unsigned*)(lds + (bufoff) + ldsw + _i * 8192), 16, 0, 0); } while (0)
; #define PG8_LDA(dst, b, h) do { _Pragma("unroll") for (int m = 0; m < 4; ++m) _Pragma("unroll") for (int k = 0; k < 2; ++k) dst[m][k] = *(const LAS bf16x8*)(lds + PG8_SA(b, h) + aoff + m * 2048 + k * 1024); } while (0)
; #define PG8_LDB(dst, b, h) do { _Pragma("unroll") for (int n = 0; n < 2; ++n) _Pragma("unroll") for (int k = 0; k < 2; ++k) dst[n][k] = *(const LAS bf16x8*)(lds + PG8_SB(b, h) + boff + n * 2048 + k * 1024); } while (0)
; #define PG8_MMA(ai, bj, At, Bt) do { __builtin_amdgcn_s_setprio(1); _Pragma("unroll") for (int m = 0; m < 4; ++m) _Pragma("unroll") for (int n = 0; n < 2; ++n) _Pragma("unroll") for (int k = 0; k < 2; ++k) \
;         acc[ai][bj][m][n] = __builtin_amdgcn_mfma_f32_16x16x32_bf16(Bt[n][k], At[m][k], acc[ai][bj][m][n], 0, 0, 0); __builtin_amdgcn_s_setprio(0); } while (0)
; #define PG8_WAIT_V(n) asm volatile("s_waitcnt vmcnt(" #n ")" ::: "memory")
; #define PG8_WAIT_L(n) asm volatile("s_waitcnt lgkmcnt(" #n ")" ::: "memory")
; #define PG8_BAR __builtin_amdgcn_s_barrier()
; #define PG8_SCHED __builtin_amdgcn_sched_barrier(0)
; template <class Epi>
; __device__ __forceinline__ void gemm_phase(LAS unsigned char* lds, const Gemm g, const StaticOrder& S, const Epi& E) {
;     ...
;             PG8_WAIT_V(8); PG8_WAIT_L(0); PG8_BAR; PG8_MMA(1, 0, At, B0); PG8_MMA(1, 1, At, B1); PG8_BAR; PG8_SCHED;
;             PG8_LDB(B0, 1, 0); PG8_LDB(B1, 1, 1); PG8_SCHED; PG8_LDA(At, 1, 0); PG8_STAGE(PG8_SA(0, 1), a2 + hstepA, voffA);
;             PG8_WAIT_V(8); PG8_WAIT_L(0); PG8_BAR; PG8_MMA(0, 0, At, B0); PG8_MMA(0, 1, At, B1); PG8_BAR; PG8_SCHED;
;             PG8_LDA(At, 1, 1); PG8_STAGE(PG8_SB(1, 0), b3, voffB); PG8_STAGE(PG8_SB(1, 1), b3 + hstepB, voffB); PG8_STAGE(PG8_SA(1, 0), a3, voffA);
;             PG8_WAIT_V(8); PG8_WAIT_L(0); PG8_BAR; PG8_MMA(1, 0, At, B0); PG8_MMA(1, 1, At, B1); PG8_BAR; PG8_SCHED;
	s_setprio 1
	s_waitcnt lgkmcnt(0)
	v_mfma_f32_16x16x32_bf16 v[62:65], v[130:133], v[162:165], v[62:65]
	v_mfma_f32_16x16x32_bf16 v[54:57], v[138:141], v[162:165], v[54:57]
	v_mfma_f32_16x16x32_bf16 v[46:49], v[130:133], v[188:191], v[46:49]
	v_mfma_f32_16x16x32_bf16 v[38:41], v[138:141], v[188:191], v[38:41]
	v_mfma_f32_16x16x32_bf16 v[30:33], v[130:133], v[196:199], v[30:33]
	v_mfma_f32_16x16x32_bf16 v[22:25], v[138:141], v[196:199], v[22:25]
	v_mfma_f32_16x16x32_bf16 v[14:17], v[130:133], v[204:207], v[14:17]
	v_mfma_f32_16x16x32_bf16 v[6:9], v[138:141], v[204:207], v[6:9]
	v_mfma_f32_16x16x32_bf16 v[62:65], v[134:137], v[174:177], v[62:65]
	v_mfma_f32_16x16x32_bf16 v[54:57], v[142:145], v[174:177], v[54:57]
	v_mfma_f32_16x16x32_bf16 v[46:49], v[134:137], v[192:195], v[46:49]
	v_mfma_f32_16x16x32_bf16 v[38:41], v[142:145], v[192:195], v[38:41]
	v_mfma_f32_16x16x32_bf16 v[30:33], v[134:137], v[200:203], v[30:33]
	v_mfma_f32_16x16x32_bf16 v[22:25], v[142:145], v[200:203], v[22:25]
	v_mfma_f32_16x16x32_bf16 v[14:17], v[134:137], v[208:211], v[14:17]
	v_mfma_f32_16x16x32_bf16 v[6:9], v[142:145], v[208:211], v[6:9]
	s_setprio 0
	s_setprio 1
	v_mfma_f32_16x16x32_bf16 v[58:61], v[146:149], v[162:165], v[58:61]
	v_mfma_f32_16x16x32_bf16 v[50:53], v[154:157], v[162:165], v[50:53]
	v_mfma_f32_16x16x32_bf16 v[42:45], v[146:149], v[188:191], v[42:45]
	v_mfma_f32_16x16x32_bf16 v[34:37], v[154:157], v[188:191], v[34:37]
	v_mfma_f32_16x16x32_bf16 v[26:29], v[146:149], v[196:199], v[26:29]
	v_mfma_f32_16x16x32_bf16 v[18:21], v[154:157], v[196:199], v[18:21]
	v_mfma_f32_16x16x32_bf16 v[10:13], v[146:149], v[204:207], v[10:13]
	v_mfma_f32_16x16x32_bf16 v[2:5], v[154:157], v[204:207], v[2:5]
	v_mfma_f32_16x16x32_bf16 v[58:61], v[150:153], v[174:177], v[58:61]
	v_mfma_f32_16x16x32_bf16 v[50:53], v[158:161], v[174:177], v[50:53]
	v_mfma_f32_16x16x32_bf16 v[42:45], v[150:153], v[192:195], v[42:45]
	v_mfma_f32_16x16x32_bf16 v[34:37], v[158:161], v[192:195], v[34:37]
	v_mfma_f32_16x16x32_bf16 v[26:29], v[150:153], v[200:203], v[26:29]
	v_mfma_f32_16x16x32_bf16 v[18:21], v[158:161], v[200:203], v[18:21]
	v_mfma_f32_16x16x32_bf16 v[10:13], v[150:153], v[208:211], v[10:13]
	v_mfma_f32_16x16x32_bf16 v[2:5], v[158:161], v[208:211], v[2:5]
	s_setprio 0
	s_barrier
	s_add_i32 s53, 0, 0x18000
	s_add_i32 s64, 0, 0x1c000
	v_add_u32_e32 v142, s53, v1
	v_add_u32_e32 v158, s64, v1
	ds_read_b128 v[130:133], v142
	ds_read_b128 v[134:137], v142 offset:1024
	ds_read_b128 v[138:141], v142 offset:2048
	ds_read_b128 v[142:145], v142 offset:3072
	ds_read_b128 v[146:149], v158
	ds_read_b128 v[150:153], v158 offset:1024
	ds_read_b128 v[154:157], v158 offset:2048
	ds_read_b128 v[158:161], v158 offset:3072
	s_add_u32 s26, s26, 0x80000
	s_addc_u32 s27, s27, 0
	s_mov_b32 m0, s30
	v_lshl_add_u64 v[216:217], s[26:27], 0, v[166:167]
	ds_read_b128 v[162:165], v181 offset:32768
	ds_read_b128 v[174:177], v181 offset:33792
	ds_read_b128 v[188:191], v181 offset:34816
	ds_read_b128 v[192:195], v181 offset:35840
	ds_read_b128 v[196:199], v181 offset:36864
	ds_read_b128 v[200:203], v181 offset:37888
	ds_read_b128 v[204:207], v181 offset:38912
	ds_read_b128 v[208:211], v181 offset:39936
	global_load_lds_dwordx4 v[216:217], off
	v_lshl_add_u64 v[216:217], s[26:27], 0, v[168:169]
	s_mov_b32 m0, s31
	s_nop 0
	global_load_lds_dwordx4 v[216:217], off
	s_waitcnt vmcnt(8)
	s_waitcnt lgkmcnt(0)
	s_barrier
	s_setprio 1
	s_waitcnt lgkmcnt(0)
	v_mfma_f32_16x16x32_bf16 v[122:125], v[130:133], v[162:165], v[122:125]
	v_mfma_f32_16x16x32_bf16 v[118:121], v[138:141], v[162:165], v[118:121]
	v_mfma_f32_16x16x32_bf16 v[110:113], v[130:133], v[188:191], v[110:113]
	v_mfma_f32_16x16x32_bf16 v[102:105], v[138:141], v[188:191], v[102:105]
	v_mfma_f32_16x16x32_bf16 v[94:97], v[130:133], v[196:199], v[94:97]
	v_mfma_f32_16x16x32_bf16 v[86:89], v[138:141], v[196:199], v[86:89]
	v_mfma_f32_16x16x32_bf16 v[78:81], v[130:133], v[204:207], v[78:81]
	v_mfma_f32_16x16x32_bf16 v[70:73], v[138:141], v[204:207], v[70:73]
	v_mfma_f32_16x16x32_bf16 v[122:125], v[134:137], v[174:177], v[122:125]
	v_mfma_f32_16x16x32_bf16 v[118:121], v[142:145], v[174:177], v[118:121]
	v_mfma_f32_16x16x32_bf16 v[110:113], v[134:137], v[192:195], v[110:113]
	v_mfma_f32_16x16x32_bf16 v[102:105], v[142:145], v[192:195], v[102:105]
	v_mfma_f32_16x16x32_bf16 v[94:97], v[134:137], v[200:203], v[94:97]
	v_mfma_f32_16x16x32_bf16 v[86:89], v[142:145], v[200:203], v[86:89]
	v_mfma_f32_16x16x32_bf16 v[78:81], v[134:137], v[208:211], v[78:81]
	v_mfma_f32_16x16x32_bf16 v[70:73], v[142:145], v[208:211], v[70:73]
	s_setprio 0
	s_setprio 1
	v_mfma_f32_16x16x32_bf16 v[126:129], v[146:149], v[162:165], v[126:129]
	v_mfma_f32_16x16x32_bf16 v[114:117], v[154:157], v[162:165], v[114:117]
	v_mfma_f32_16x16x32_bf16 v[106:109], v[146:149], v[188:191], v[106:109]
	v_mfma_f32_16x16x32_bf16 v[98:101], v[154:157], v[188:191], v[98:101]
	v_mfma_f32_16x16x32_bf16 v[90:93], v[146:149], v[196:199], v[90:93]
	v_mfma_f32_16x16x32_bf16 v[82:85], v[154:157], v[196:199], v[82:85]
	v_mfma_f32_16x16x32_bf16 v[74:77], v[146:149], v[204:207], v[74:77]
	v_mfma_f32_16x16x32_bf16 v[66:69], v[154:157], v[204:207], v[66:69]
	v_mfma_f32_16x16x32_bf16 v[126:129], v[150:153], v[174:177], v[126:129]
	v_mfma_f32_16x16x32_bf16 v[114:117], v[158:161], v[174:177], v[114:117]
	v_mfma_f32_16x16x32_bf16 v[106:109], v[150:153], v[192:195], v[106:109]
	v_mfma_f32_16x16x32_bf16 v[98:101], v[158:161], v[192:195], v[98:101]
	v_mfma_f32_16x16x32_bf16 v[90:93], v[150:153], v[200:203], v[90:93]
	v_mfma_f32_16x16x32_bf16 v[82:85], v[158:161], v[200:203], v[82:85]
	v_mfma_f32_16x16x32_bf16 v[74:77], v[150:153], v[208:211], v[74:77]
	v_mfma_f32_16x16x32_bf16 v[66:69], v[158:161], v[208:211], v[66:69]
	s_setprio 0
	s_barrier
; #define PG8_STAGE(bufoff, gbase, voff) do { _Pragma("unroll") for (int _i = 0; _i < 2; ++_i) \
;         __builtin_amdgcn_global_load_lds((const unsigned*)((const char*)(gbase) + (voff)[_i]), (LAS unsigned*)(lds + (bufoff) + ldsw + _i * 8192), 16, 0, 0); } while (0)
; #define PG8_LDA(dst, b, h) do { _Pragma("unroll") for (int m = 0; m < 4; ++m) _Pragma("unroll") for (int k = 0; k < 2; ++k) dst[m][k] = *(const LAS bf16x8*)(lds + PG8_SA(b, h) + aoff + m * 2048 + k * 1024); } while (0)
; #define PG8_MMA(ai, bj, At, Bt) do { __builtin_amdgcn_s_setprio(1); _Pragma("unroll") for (int m = 0; m < 4; ++m) _Pragma("unroll") for (int n = 0; n < 2; ++n) _Pragma("unroll") for (int k = 0; k < 2; ++k) \
;         acc[ai][bj][m][n] = __builtin_amdgcn_mfma_f32_16x16x32_bf16(Bt[n][k], At[m][k], acc[ai][bj][m][n], 0, 0, 0); __builtin_amdgcn_s_setprio(0); } while (0)
; #define PG8_WAIT_V(n) asm volatile("s_waitcnt vmcnt(" #n ")" ::: "memory")
; #define PG8_WAIT_L(n) asm volatile("s_waitcnt lgkmcnt(" #n ")" ::: "memory")
; #define PG8_BAR __builtin_amdgcn_s_barrier()
; #define PG8_SCHED __builtin_amdgcn_sched_barrier(0)
; template <class Epi>
; __device__ __forceinline__ void gemm_phase(LAS unsigned char* lds, const Gemm g, const StaticOrder& S, const Epi& E) {
;     ...
;             PG8_LDA(At, 1, 1); PG8_STAGE(PG8_SB(1, 0), b3, voffB); PG8_STAGE(PG8_SB(1, 1), b3 + hstepB, voffB); PG8_STAGE(PG8_SA(1, 0), a3, voffA);
;             PG8_WAIT_V(8); PG8_WAIT_L(0); PG8_BAR; PG8_MMA(1, 0, At, B0); PG8_MMA(1, 1, At, B1); PG8_BAR; PG8_SCHED;
;         }
;         if (wr == 0) PG8_BAR;
	s_add_i32 s26, s53, s28
	v_lshl_add_u64 v[178:179], v[178:179], 0, s[84:85]
	s_mov_b32 m0, s26
	ds_read_b128 v[162:165], v181 offset:49152
	ds_read_b128 v[174:177], v181 offset:50176
	ds_read_b128 v[188:191], v181 offset:51200
	ds_read_b128 v[192:195], v181 offset:52224
	ds_read_b128 v[196:199], v181 offset:53248
	ds_read_b128 v[200:203], v181 offset:54272
	ds_read_b128 v[204:207], v181 offset:55296
	ds_read_b128 v[208:211], v181 offset:56320
	global_load_lds_dwordx4 v[178:179], off
	s_add_i32 m0, s26, 0x2000
	s_add_u32 s14, s14, 0x80080
	v_lshl_add_u64 v[178:179], v[184:185], 0, s[84:85]
	s_addc_u32 s15, s15, 0
	s_add_i32 s26, s64, s28
	global_load_lds_dwordx4 v[178:179], off
	v_lshl_add_u64 v[178:179], s[14:15], 0, v[166:167]
	s_mov_b32 m0, s26
	s_nop 0
	global_load_lds_dwordx4 v[178:179], off
	v_lshl_add_u64 v[178:179], s[14:15], 0, v[168:169]
	s_add_i32 m0, s26, 0x2000
	s_nop 0
	global_load_lds_dwordx4 v[178:179], off
	v_lshl_add_u64 v[178:179], v[212:213], 0, s[84:85]
	s_mov_b32 m0, s35
	s_nop 0
	global_load_lds_dwordx4 v[178:179], off
	v_lshl_add_u64 v[178:179], v[214:215], 0, s[84:85]
	s_mov_b32 m0, s42
	s_nop 0
	global_load_lds_dwordx4 v[178:179], off
	s_waitcnt vmcnt(8)
	s_waitcnt lgkmcnt(0)
	s_barrier
	s_setprio 1
	s_waitcnt lgkmcnt(0)
	v_mfma_f32_16x16x32_bf16 v[62:65], v[130:133], v[162:165], v[62:65]
	v_mfma_f32_16x16x32_bf16 v[54:57], v[138:141], v[162:165], v[54:57]
	v_mfma_f32_16x16x32_bf16 v[46:49], v[130:133], v[188:191], v[46:49]
	v_mfma_f32_16x16x32_bf16 v[38:41], v[138:141], v[188:191], v[38:41]
	v_mfma_f32_16x16x32_bf16 v[30:33], v[130:133], v[196:199], v[30:33]
	v_mfma_f32_16x16x32_bf16 v[22:25], v[138:141], v[196:199], v[22:25]
	v_mfma_f32_16x16x32_bf16 v[14:17], v[130:133], v[204:207], v[14:17]
	v_mfma_f32_16x16x32_bf16 v[6:9], v[138:141], v[204:207], v[6:9]
	v_mfma_f32_16x16x32_bf16 v[62:65], v[134:137], v[174:177], v[62:65]
	v_mfma_f32_16x16x32_bf16 v[54:57], v[142:145], v[174:177], v[54:57]
	v_mfma_f32_16x16x32_bf16 v[46:49], v[134:137], v[192:195], v[46:49]
	v_mfma_f32_16x16x32_bf16 v[38:41], v[142:145], v[192:195], v[38:41]
	v_mfma_f32_16x16x32_bf16 v[30:33], v[134:137], v[200:203], v[30:33]
	v_mfma_f32_16x16x32_bf16 v[22:25], v[142:145], v[200:203], v[22:25]
	v_mfma_f32_16x16x32_bf16 v[14:17], v[134:137], v[208:211], v[14:17]
	v_mfma_f32_16x16x32_bf16 v[6:9], v[142:145], v[208:211], v[6:9]
	s_setprio 0
	s_setprio 1
	v_mfma_f32_16x16x32_bf16 v[58:61], v[146:149], v[162:165], v[58:61]
	v_mfma_f32_16x16x32_bf16 v[50:53], v[154:157], v[162:165], v[50:53]
	v_mfma_f32_16x16x32_bf16 v[42:45], v[146:149], v[188:191], v[42:45]
	v_mfma_f32_16x16x32_bf16 v[34:37], v[154:157], v[188:191], v[34:37]
	v_mfma_f32_16x16x32_bf16 v[26:29], v[146:149], v[196:199], v[26:29]
	v_mfma_f32_16x16x32_bf16 v[18:21], v[154:157], v[196:199], v[18:21]
	v_mfma_f32_16x16x32_bf16 v[10:13], v[146:149], v[204:207], v[10:13]
	v_mfma_f32_16x16x32_bf16 v[2:5], v[154:157], v[204:207], v[2:5]
	v_mfma_f32_16x16x32_bf16 v[58:61], v[150:153], v[174:177], v[58:61]
	v_mfma_f32_16x16x32_bf16 v[50:53], v[158:161], v[174:177], v[50:53]
	v_mfma_f32_16x16x32_bf16 v[42:45], v[150:153], v[192:195], v[42:45]
	v_mfma_f32_16x16x32_bf16 v[34:37], v[158:161], v[192:195], v[34:37]
	v_mfma_f32_16x16x32_bf16 v[26:29], v[150:153], v[200:203], v[26:29]
	v_mfma_f32_16x16x32_bf16 v[18:21], v[158:161], v[200:203], v[18:21]
	v_mfma_f32_16x16x32_bf16 v[10:13], v[150:153], v[208:211], v[10:13]
	v_mfma_f32_16x16x32_bf16 v[2:5], v[158:161], v[208:211], v[2:5]
	s_setprio 0
	s_barrier
	s_add_i32 s41, s41, 2
	s_add_u32 s24, s24, 0x100
	s_addc_u32 s25, s25, 0
	s_add_u32 s40, s40, 0x100
	s_addc_u32 s52, s52, 0
	s_cmp_gt_u32 s41, 29
	s_cbranch_scc0 .LBB0_1324
	s_cmp_ge_u32 s74, 16
	s_cbranch_scc1 .Lwpf_b
	s_lshl_b32 s100, s74, 9
	v_add_u32_e32 v130, s100, v246
	v_lshrrev_b32_e32 v131, 2, v130
	v_and_b32_e32 v130, 3, v130
	v_lshlrev_b32_e32 v130, 7, v130
	v_lshl_add_u32 v130, v131, 12, v130
	s_add_u32 s100, s88, 0x1800000
	s_addc_u32 s101, s89, 0
	s_mov_b32 m0, 0x21000
	s_nop 0
	global_load_lds_dword v130, s[100:101]
.Lwpf_b:
	s_and_b64 vcc, exec, s[10:11]
	s_cbranch_vccz .LBB0_1327
	s_barrier

; #define PG8_STAGE(bufoff, gbase, voff) do { _Pragma("unroll") for (int _i = 0; _i < 2; ++_i) \
;         __builtin_amdgcn_global_load_lds((const unsigned*)((const char*)(gbase) + (voff)[_i]), (LAS unsigned*)(lds + (bufoff) + ldsw + _i * 8192), 16, 0, 0); } while (0)
; #define PG8_LDA(dst, b, h) do { _Pragma("unroll") for (int m = 0; m < 4; ++m) _Pragma("unroll") for (int k = 0; k < 2; ++k) dst[m][k] = *(const LAS bf16x8*)(lds + PG8_SA(b, h) + aoff + m * 2048 + k * 1024); } while (0)
; #define PG8_LDB(dst, b, h) do { _Pragma("unroll") for (int n = 0; n < 2; ++n) _Pragma("unroll") for (int k = 0; k < 2; ++k) dst[n][k] = *(const LAS bf16x8*)(lds + PG8_SB(b, h) + boff + n * 2048 + k * 1024); } while (0)
; #define PG8_MMA(ai, bj, At, Bt) do { __builtin_amdgcn_s_setprio(1); _Pragma("unroll") for (int m = 0; m < 4; ++m) _Pragma("unroll") for (int n = 0; n < 2; ++n) _Pragma("unroll") for (int k = 0; k < 2; ++k) \
;         acc[ai][bj][m][n] = __builtin_amdgcn_mfma_f32_16x16x32_bf16(Bt[n][k], At[m][k], acc[ai][bj][m][n], 0, 0, 0); __builtin_amdgcn_s_setprio(0); } while (0)
; #define PG8_WAIT_V(n) asm volatile("s_waitcnt vmcnt(" #n ")" ::: "memory")
; #define PG8_WAIT_L(n) asm volatile("s_waitcnt lgkmcnt(" #n ")" ::: "memory")
; #define PG8_BAR __builtin_amdgcn_s_barrier()
; #define PG8_SCHED __builtin_amdgcn_sched_barrier(0)
; template <class Epi>
; __device__ __forceinline__ void gemm_phase(LAS unsigned char* lds, const Gemm g, const StaticOrder& S, const Epi& E) {
;     ...
;             const bool last = (t == nt - 2);
;             const char* a1 = cA + (size_t)(t + 1) * kstep;
;             const char* a2 = last ? nA : cA + (size_t)(t + 2) * kstep; const char* b2 = last ? nB : cB + (size_t)(t + 2) * kstep;
;             const char* a3 = a2 + kstep; const char* b3 = b2 + kstep;
;             PG8_LDB(B0, 0, 0); PG8_LDB(B1, 0, 1); PG8_SCHED; PG8_LDA(At, 0, 0); PG8_STAGE(PG8_SA(1, 1), a1 + hstepA, voffA);
;             PG8_WAIT_V(8); PG8_WAIT_L(0); PG8_BAR; PG8_MMA(0, 0, At, B0); PG8_MMA(0, 1, At, B1); PG8_BAR; PG8_SCHED;
;             PG8_LDA(At, 0, 1); PG8_STAGE(PG8_SB(0, 0), b2, voffB); PG8_STAGE(PG8_SB(0, 1), b2 + hstepB, voffB); PG8_STAGE(PG8_SA(0, 0), a2, voffA);
;             PG8_WAIT_V(8); PG8_WAIT_L(0); PG8_BAR; PG8_MMA(1, 0, At, B0); PG8_MMA(1, 1, At, B1); PG8_BAR; PG8_SCHED;
.LBB0_2035:
	s_add_u32 s14, s24, 0xfff80080
	s_addc_u32 s15, s25, -1
	s_add_i32 s41, 0, 0x10000
	s_cmp_eq_u32 s52, 28
	s_cselect_b32 s27, s1, s15
	s_cselect_b32 s26, s3, s14
	s_cselect_b32 s15, s7, s40
	s_cselect_b32 s14, s13, s17
	s_add_i32 s53, 0, 0x14000
	v_add_u32_e32 v142, s41, v1
	v_add_u32_e32 v158, s53, v1
	ds_read_b128 v[130:133], v142
	ds_read_b128 v[134:137], v142 offset:1024
	ds_read_b128 v[138:141], v142 offset:2048
	ds_read_b128 v[142:145], v142 offset:3072
	ds_read_b128 v[146:149], v158
	ds_read_b128 v[150:153], v158 offset:1024
	ds_read_b128 v[154:157], v158 offset:2048
	ds_read_b128 v[158:161], v158 offset:3072
	v_lshl_add_u64 v[178:179], s[24:25], 0, v[196:197]
	s_add_i32 m0, s23, 0xc000
	ds_read_b128 v[162:165], v181
	ds_read_b128 v[166:169], v181 offset:1024
	ds_read_b128 v[170:173], v181 offset:2048
	ds_read_b128 v[174:177], v181 offset:3072
	ds_read_b128 v[200:203], v181 offset:4096
	ds_read_b128 v[204:207], v181 offset:5120
	ds_read_b128 v[208:211], v181 offset:6144
	ds_read_b128 v[212:215], v181 offset:7168
	global_load_lds_dwordx4 v[178:179], off
	v_lshl_add_u64 v[178:179], s[24:25], 0, v[198:199]
	s_add_i32 m0, s23, 0xe000
	s_nop 0
	global_load_lds_dwordx4 v[178:179], off
	s_waitcnt vmcnt(8)
	s_waitcnt lgkmcnt(0)
	s_barrier
	s_setprio 1
	s_waitcnt lgkmcnt(0)
	v_mfma_f32_16x16x32_bf16 v[126:129], v[130:133], v[162:165], v[126:129]
	v_mfma_f32_16x16x32_bf16 v[122:125], v[138:141], v[162:165], v[122:125]
	v_mfma_f32_16x16x32_bf16 v[110:113], v[130:133], v[170:173], v[110:113]
	v_mfma_f32_16x16x32_bf16 v[106:109], v[138:141], v[170:173], v[106:109]
	v_mfma_f32_16x16x32_bf16 v[94:97], v[130:133], v[200:203], v[94:97]
	v_mfma_f32_16x16x32_bf16 v[90:93], v[138:141], v[200:203], v[90:93]
	v_mfma_f32_16x16x32_bf16 v[82:85], v[130:133], v[208:211], v[82:85]
	v_mfma_f32_16x16x32_bf16 v[74:77], v[138:141], v[208:211], v[74:77]
	v_mfma_f32_16x16x32_bf16 v[126:129], v[134:137], v[166:169], v[126:129]
	v_mfma_f32_16x16x32_bf16 v[122:125], v[142:145], v[166:169], v[122:125]
	v_mfma_f32_16x16x32_bf16 v[110:113], v[134:137], v[174:177], v[110:113]
	v_mfma_f32_16x16x32_bf16 v[106:109], v[142:145], v[174:177], v[106:109]
	v_mfma_f32_16x16x32_bf16 v[94:97], v[134:137], v[204:207], v[94:97]
	v_mfma_f32_16x16x32_bf16 v[90:93], v[142:145], v[204:207], v[90:93]
	v_mfma_f32_16x16x32_bf16 v[82:85], v[134:137], v[212:215], v[82:85]
	v_mfma_f32_16x16x32_bf16 v[74:77], v[142:145], v[212:215], v[74:77]
	s_setprio 0
	s_setprio 1
	v_mfma_f32_16x16x32_bf16 v[118:121], v[146:149], v[162:165], v[118:121]
	v_mfma_f32_16x16x32_bf16 v[114:117], v[154:157], v[162:165], v[114:117]
	v_mfma_f32_16x16x32_bf16 v[102:105], v[146:149], v[170:173], v[102:105]
	v_mfma_f32_16x16x32_bf16 v[98:101], v[154:157], v[170:173], v[98:101]
	v_mfma_f32_16x16x32_bf16 v[86:89], v[146:149], v[200:203], v[86:89]
	v_mfma_f32_16x16x32_bf16 v[78:81], v[154:157], v[200:203], v[78:81]
	v_mfma_f32_16x16x32_bf16 v[70:73], v[146:149], v[208:211], v[70:73]
	v_mfma_f32_16x16x32_bf16 v[66:69], v[154:157], v[208:211], v[66:69]
	v_mfma_f32_16x16x32_bf16 v[118:121], v[150:153], v[166:169], v[118:121]
	v_mfma_f32_16x16x32_bf16 v[114:117], v[158:161], v[166:169], v[114:117]
	v_mfma_f32_16x16x32_bf16 v[102:105], v[150:153], v[174:177], v[102:105]
	v_mfma_f32_16x16x32_bf16 v[98:101], v[158:161], v[174:177], v[98:101]
	v_mfma_f32_16x16x32_bf16 v[86:89], v[150:153], v[204:207], v[86:89]
	v_mfma_f32_16x16x32_bf16 v[78:81], v[158:161], v[204:207], v[78:81]
	v_mfma_f32_16x16x32_bf16 v[70:73], v[150:153], v[212:215], v[70:73]
	v_mfma_f32_16x16x32_bf16 v[66:69], v[158:161], v[212:215], v[66:69]
	s_setprio 0
	s_barrier
	s_add_i32 s41, s41, s30
	v_lshl_add_u64 v[178:179], s[14:15], 0, v[190:191]
	s_mov_b32 m0, s41
	ds_read_b128 v[162:165], v181 offset:16384
	ds_read_b128 v[166:169], v181 offset:17408
	ds_read_b128 v[170:173], v181 offset:18432
	ds_read_b128 v[174:177], v181 offset:19456
	ds_read_b128 v[200:203], v181 offset:20480
	ds_read_b128 v[204:207], v181 offset:21504
	ds_read_b128 v[208:211], v181 offset:22528
	ds_read_b128 v[212:215], v181 offset:23552
	global_load_lds_dwordx4 v[178:179], off
	s_add_i32 m0, s41, 0x2000
	s_add_u32 s62, s14, 0x80000
	v_lshl_add_u64 v[184:185], s[14:15], 0, v[194:195]
	s_addc_u32 s63, s15, 0
	s_add_i32 s41, s53, s30
	global_load_lds_dwordx4 v[184:185], off
	v_lshl_add_u64 v[216:217], s[62:63], 0, v[190:191]
	s_mov_b32 m0, s41
	v_lshl_add_u64 v[218:219], s[26:27], 0, v[192:193]
	global_load_lds_dwordx4 v[216:217], off
	v_lshl_add_u64 v[216:217], s[62:63], 0, v[194:195]
	s_add_i32 m0, s41, 0x2000
	s_nop 0
	global_load_lds_dwordx4 v[216:217], off
	v_lshl_add_u64 v[216:217], s[26:27], 0, v[188:189]
	s_mov_b32 m0, s23
	s_nop 0
	global_load_lds_dwordx4 v[216:217], off
	s_mov_b32 m0, s34
	s_nop 0
	global_load_lds_dwordx4 v[218:219], off
	s_waitcnt vmcnt(8)
	s_waitcnt lgkmcnt(0)
	s_barrier
; #define PG8_STAGE(bufoff, gbase, voff) do { _Pragma("unroll") for (int _i = 0; _i < 2; ++_i) \
;         __builtin_amdgcn_global_load_lds((const unsigned*)((const char*)(gbase) + (voff)[_i]), (LAS unsigned*)(lds + (bufoff) + ldsw + _i * 8192), 16, 0, 0); } while (0)
; #define PG8_LDA(dst, b, h) do { _Pragma("unroll") for (int m = 0; m < 4; ++m) _Pragma("unroll") for (int k = 0; k < 2; ++k) dst[m][k] = *(const LAS bf16x8*)(lds + PG8_SA(b, h) + aoff + m * 2048 + k * 1024); } while (0)
; #define PG8_LDB(dst, b, h) do { _Pragma("unroll") for (int n = 0; n < 2; ++n) _Pragma("unroll") for (int k = 0; k < 2; ++k) dst[n][k] = *(const LAS bf16x8*)(lds + PG8_SB(b, h) + boff + n * 2048 + k * 1024); } while (0)
; #define PG8_MMA(ai, bj, At, Bt) do { __builtin_amdgcn_s_setprio(1); _Pragma("unroll") for (int m = 0; m < 4; ++m) _Pragma("unroll") for (int n = 0; n < 2; ++n) _Pragma("unroll") for (int k = 0; k < 2; ++k) \
;         acc[ai][bj][m][n] = __builtin_amdgcn_mfma_f32_16x16x32_bf16(Bt[n][k], At[m][k], acc[ai][bj][m][n], 0, 0, 0); __builtin_amdgcn_s_setprio(0); } while (0)
; #define PG8_WAIT_V(n) asm volatile("s_waitcnt vmcnt(" #n ")" ::: "memory")
; #define PG8_WAIT_L(n) asm volatile("s_waitcnt lgkmcnt(" #n ")" ::: "memory")
; #define PG8_BAR __builtin_amdgcn_s_barrier()
; #define PG8_SCHED __builtin_amdgcn_sched_barrier(0)
; template <class Epi>
; __device__ __forceinline__ void gemm_phase(LAS unsigned char* lds, const Gemm g, const StaticOrder& S, const Epi& E) {
;     ...
;             PG8_WAIT_V(8); PG8_WAIT_L(0); PG8_BAR; PG8_MMA(1, 0, At, B0); PG8_MMA(1, 1, At, B1); PG8_BAR; PG8_SCHED;
;             PG8_LDB(B0, 1, 0); PG8_LDB(B1, 1, 1); PG8_SCHED; PG8_LDA(At, 1, 0); PG8_STAGE(PG8_SA(0, 1), a2 + hstepA, voffA);
;             PG8_WAIT_V(8); PG8_WAIT_L(0); PG8_BAR; PG8_MMA(0, 0, At, B0); PG8_MMA(0, 1, At, B1); PG8_BAR; PG8_SCHED;
;             PG8_LDA(At, 1, 1); PG8_STAGE(PG8_SB(1, 0), b3, voffB); PG8_STAGE(PG8_SB(1, 1), b3 + hstepB, voffB); PG8_STAGE(PG8_SA(1, 0), a3, voffA);
;             PG8_WAIT_V(8); PG8_WAIT_L(0); PG8_BAR; PG8_MMA(1, 0, At, B0); PG8_MMA(1, 1, At, B1); PG8_BAR; PG8_SCHED;
	s_setprio 1
	s_waitcnt lgkmcnt(0)
	v_mfma_f32_16x16x32_bf16 v[62:65], v[130:133], v[162:165], v[62:65]
	v_mfma_f32_16x16x32_bf16 v[58:61], v[138:141], v[162:165], v[58:61]
	v_mfma_f32_16x16x32_bf16 v[50:53], v[130:133], v[170:173], v[50:53]
	v_mfma_f32_16x16x32_bf16 v[42:45], v[138:141], v[170:173], v[42:45]
	v_mfma_f32_16x16x32_bf16 v[30:33], v[130:133], v[200:203], v[30:33]
	v_mfma_f32_16x16x32_bf16 v[26:29], v[138:141], v[200:203], v[26:29]
	v_mfma_f32_16x16x32_bf16 v[18:21], v[130:133], v[208:211], v[18:21]
	v_mfma_f32_16x16x32_bf16 v[10:13], v[138:141], v[208:211], v[10:13]
	v_mfma_f32_16x16x32_bf16 v[62:65], v[134:137], v[166:169], v[62:65]
	v_mfma_f32_16x16x32_bf16 v[58:61], v[142:145], v[166:169], v[58:61]
	v_mfma_f32_16x16x32_bf16 v[50:53], v[134:137], v[174:177], v[50:53]
	v_mfma_f32_16x16x32_bf16 v[42:45], v[142:145], v[174:177], v[42:45]
	v_mfma_f32_16x16x32_bf16 v[30:33], v[134:137], v[204:207], v[30:33]
	v_mfma_f32_16x16x32_bf16 v[26:29], v[142:145], v[204:207], v[26:29]
	v_mfma_f32_16x16x32_bf16 v[18:21], v[134:137], v[212:215], v[18:21]
	v_mfma_f32_16x16x32_bf16 v[10:13], v[142:145], v[212:215], v[10:13]
	s_setprio 0
	s_setprio 1
	v_mfma_f32_16x16x32_bf16 v[54:57], v[146:149], v[162:165], v[54:57]
	v_mfma_f32_16x16x32_bf16 v[46:49], v[154:157], v[162:165], v[46:49]
	v_mfma_f32_16x16x32_bf16 v[38:41], v[146:149], v[170:173], v[38:41]
	v_mfma_f32_16x16x32_bf16 v[34:37], v[154:157], v[170:173], v[34:37]
	v_mfma_f32_16x16x32_bf16 v[22:25], v[146:149], v[200:203], v[22:25]
	v_mfma_f32_16x16x32_bf16 v[14:17], v[154:157], v[200:203], v[14:17]
	v_mfma_f32_16x16x32_bf16 v[6:9], v[146:149], v[208:211], v[6:9]
	v_mfma_f32_16x16x32_bf16 v[2:5], v[154:157], v[208:211], v[2:5]
	v_mfma_f32_16x16x32_bf16 v[54:57], v[150:153], v[166:169], v[54:57]
	v_mfma_f32_16x16x32_bf16 v[46:49], v[158:161], v[166:169], v[46:49]
	v_mfma_f32_16x16x32_bf16 v[38:41], v[150:153], v[174:177], v[38:41]
	v_mfma_f32_16x16x32_bf16 v[34:37], v[158:161], v[174:177], v[34:37]
	v_mfma_f32_16x16x32_bf16 v[22:25], v[150:153], v[204:207], v[22:25]
	v_mfma_f32_16x16x32_bf16 v[14:17], v[158:161], v[204:207], v[14:17]
	v_mfma_f32_16x16x32_bf16 v[6:9], v[150:153], v[212:215], v[6:9]
	v_mfma_f32_16x16x32_bf16 v[2:5], v[158:161], v[212:215], v[2:5]
	s_setprio 0
	s_barrier
	s_add_i32 s41, 0, 0x18000
	s_add_i32 s53, 0, 0x1c000
	v_add_u32_e32 v142, s41, v1
	v_add_u32_e32 v158, s53, v1
	ds_read_b128 v[130:133], v142
	ds_read_b128 v[134:137], v142 offset:1024
	ds_read_b128 v[138:141], v142 offset:2048
	ds_read_b128 v[142:145], v142 offset:3072
	ds_read_b128 v[146:149], v158
	ds_read_b128 v[150:153], v158 offset:1024
	ds_read_b128 v[154:157], v158 offset:2048
	ds_read_b128 v[158:161], v158 offset:3072
	s_add_u32 s26, s26, 0x80000
	s_addc_u32 s27, s27, 0
	s_mov_b32 m0, s35
	v_lshl_add_u64 v[220:221], s[26:27], 0, v[188:189]
	ds_read_b128 v[162:165], v181 offset:32768
	ds_read_b128 v[166:169], v181 offset:33792
	ds_read_b128 v[170:173], v181 offset:34816
	ds_read_b128 v[174:177], v181 offset:35840
	ds_read_b128 v[200:203], v181 offset:36864
	ds_read_b128 v[204:207], v181 offset:37888
	ds_read_b128 v[208:211], v181 offset:38912
	ds_read_b128 v[212:215], v181 offset:39936
	global_load_lds_dwordx4 v[220:221], off
	v_lshl_add_u64 v[220:221], s[26:27], 0, v[192:193]
	s_mov_b32 m0, s42
	s_nop 0
	global_load_lds_dwordx4 v[220:221], off
	s_waitcnt vmcnt(8)
	s_waitcnt lgkmcnt(0)
	s_barrier
	s_setprio 1
	s_waitcnt lgkmcnt(0)
	v_mfma_f32_16x16x32_bf16 v[126:129], v[130:133], v[162:165], v[126:129]
	v_mfma_f32_16x16x32_bf16 v[122:125], v[138:141], v[162:165], v[122:125]
	v_mfma_f32_16x16x32_bf16 v[110:113], v[130:133], v[170:173], v[110:113]
	v_mfma_f32_16x16x32_bf16 v[106:109], v[138:141], v[170:173], v[106:109]
	v_mfma_f32_16x16x32_bf16 v[94:97], v[130:133], v[200:203], v[94:97]
	v_mfma_f32_16x16x32_bf16 v[90:93], v[138:141], v[200:203], v[90:93]
	v_mfma_f32_16x16x32_bf16 v[82:85], v[130:133], v[208:211], v[82:85]
	v_mfma_f32_16x16x32_bf16 v[74:77], v[138:141], v[208:211], v[74:77]
	v_mfma_f32_16x16x32_bf16 v[126:129], v[134:137], v[166:169], v[126:129]
	v_mfma_f32_16x16x32_bf16 v[122:125], v[142:145], v[166:169], v[122:125]
	v_mfma_f32_16x16x32_bf16 v[110:113], v[134:137], v[174:177], v[110:113]
	v_mfma_f32_16x16x32_bf16 v[106:109], v[142:145], v[174:177], v[106:109]
	v_mfma_f32_16x16x32_bf16 v[94:97], v[134:137], v[204:207], v[94:97]
	v_mfma_f32_16x16x32_bf16 v[90:93], v[142:145], v[204:207], v[90:93]
	v_mfma_f32_16x16x32_bf16 v[82:85], v[134:137], v[212:215], v[82:85]
	v_mfma_f32_16x16x32_bf16 v[74:77], v[142:145], v[212:215], v[74:77]
	s_setprio 0
	s_setprio 1
	v_mfma_f32_16x16x32_bf16 v[118:121], v[146:149], v[162:165], v[118:121]
	v_mfma_f32_16x16x32_bf16 v[114:117], v[154:157], v[162:165], v[114:117]
	v_mfma_f32_16x16x32_bf16 v[102:105], v[146:149], v[170:173], v[102:105]
	v_mfma_f32_16x16x32_bf16 v[98:101], v[154:157], v[170:173], v[98:101]
	v_mfma_f32_16x16x32_bf16 v[86:89], v[146:149], v[200:203], v[86:89]
	v_mfma_f32_16x16x32_bf16 v[78:81], v[154:157], v[200:203], v[78:81]
	v_mfma_f32_16x16x32_bf16 v[70:73], v[146:149], v[208:211], v[70:73]
	v_mfma_f32_16x16x32_bf16 v[66:69], v[154:157], v[208:211], v[66:69]
	v_mfma_f32_16x16x32_bf16 v[118:121], v[150:153], v[166:169], v[118:121]
	v_mfma_f32_16x16x32_bf16 v[114:117], v[158:161], v[166:169], v[114:117]
	v_mfma_f32_16x16x32_bf16 v[102:105], v[150:153], v[174:177], v[102:105]
	v_mfma_f32_16x16x32_bf16 v[98:101], v[158:161], v[174:177], v[98:101]
	v_mfma_f32_16x16x32_bf16 v[86:89], v[150:153], v[204:207], v[86:89]
	v_mfma_f32_16x16x32_bf16 v[78:81], v[158:161], v[204:207], v[78:81]
	v_mfma_f32_16x16x32_bf16 v[70:73], v[150:153], v[212:215], v[70:73]
	v_mfma_f32_16x16x32_bf16 v[66:69], v[158:161], v[212:215], v[66:69]
	s_setprio 0
	s_barrier
; #define PG8_STAGE(bufoff, gbase, voff) do { _Pragma("unroll") for (int _i = 0; _i < 2; ++_i) \
;         __builtin_amdgcn_global_load_lds((const unsigned*)((const char*)(gbase) + (voff)[_i]), (LAS unsigned*)(lds + (bufoff) + ldsw + _i * 8192), 16, 0, 0); } while (0)
; #define PG8_LDA(dst, b, h) do { _Pragma("unroll") for (int m = 0; m < 4; ++m) _Pragma("unroll") for (int k = 0; k < 2; ++k) dst[m][k] = *(const LAS bf16x8*)(lds + PG8_SA(b, h) + aoff + m * 2048 + k * 1024); } while (0)
; #define PG8_MMA(ai, bj, At, Bt) do { __builtin_amdgcn_s_setprio(1); _Pragma("unroll") for (int m = 0; m < 4; ++m) _Pragma("unroll") for (int n = 0; n < 2; ++n) _Pragma("unroll") for (int k = 0; k < 2; ++k) \
;         acc[ai][bj][m][n] = __builtin_amdgcn_mfma_f32_16x16x32_bf16(Bt[n][k], At[m][k], acc[ai][bj][m][n], 0, 0, 0); __builtin_amdgcn_s_setprio(0); } while (0)
; #define PG8_WAIT_V(n) asm volatile("s_waitcnt vmcnt(" #n ")" ::: "memory")
; #define PG8_WAIT_L(n) asm volatile("s_waitcnt lgkmcnt(" #n ")" ::: "memory")
; #define PG8_BAR __builtin_amdgcn_s_barrier()
; #define PG8_SCHED __builtin_amdgcn_sched_barrier(0)
; template <class Epi>
; __device__ __forceinline__ void gemm_phase(LAS unsigned char* lds, const Gemm g, const StaticOrder& S, const Epi& E) {
;     ...
;             PG8_LDA(At, 1, 1); PG8_STAGE(PG8_SB(1, 0), b3, voffB); PG8_STAGE(PG8_SB(1, 1), b3 + hstepB, voffB); PG8_STAGE(PG8_SA(1, 0), a3, voffA);
;             PG8_WAIT_V(8); PG8_WAIT_L(0); PG8_BAR; PG8_MMA(1, 0, At, B0); PG8_MMA(1, 1, At, B1); PG8_BAR; PG8_SCHED;
;         }
;         if (wr == 0) PG8_BAR;
	s_add_i32 s26, s41, s30
	v_lshl_add_u64 v[178:179], v[178:179], 0, s[84:85]
	s_mov_b32 m0, s26
	ds_read_b128 v[162:165], v181 offset:49152
	ds_read_b128 v[166:169], v181 offset:50176
	ds_read_b128 v[170:173], v181 offset:51200
	ds_read_b128 v[174:177], v181 offset:52224
	ds_read_b128 v[200:203], v181 offset:53248
	ds_read_b128 v[204:207], v181 offset:54272
	ds_read_b128 v[208:211], v181 offset:55296
	ds_read_b128 v[212:215], v181 offset:56320
	global_load_lds_dwordx4 v[178:179], off
	s_add_i32 m0, s26, 0x2000
	s_add_u32 s14, s14, 0x80080
	v_lshl_add_u64 v[178:179], v[184:185], 0, s[84:85]
	s_addc_u32 s15, s15, 0
	s_add_i32 s26, s53, s30
	global_load_lds_dwordx4 v[178:179], off
	v_lshl_add_u64 v[178:179], s[14:15], 0, v[190:191]
	s_mov_b32 m0, s26
	s_nop 0
	global_load_lds_dwordx4 v[178:179], off
	v_lshl_add_u64 v[178:179], s[14:15], 0, v[194:195]
	s_add_i32 m0, s26, 0x2000
	s_nop 0
	global_load_lds_dwordx4 v[178:179], off
	v_lshl_add_u64 v[178:179], v[216:217], 0, s[84:85]
	s_mov_b32 m0, s68
	s_nop 0
	global_load_lds_dwordx4 v[178:179], off
	v_lshl_add_u64 v[178:179], v[218:219], 0, s[84:85]
	s_mov_b32 m0, s69
	s_nop 0
	global_load_lds_dwordx4 v[178:179], off
	s_waitcnt vmcnt(8)
	s_waitcnt lgkmcnt(0)
	s_barrier
	s_setprio 1
	s_waitcnt lgkmcnt(0)
	v_mfma_f32_16x16x32_bf16 v[62:65], v[130:133], v[162:165], v[62:65]
	v_mfma_f32_16x16x32_bf16 v[58:61], v[138:141], v[162:165], v[58:61]
	v_mfma_f32_16x16x32_bf16 v[50:53], v[130:133], v[170:173], v[50:53]
	v_mfma_f32_16x16x32_bf16 v[42:45], v[138:141], v[170:173], v[42:45]
	v_mfma_f32_16x16x32_bf16 v[30:33], v[130:133], v[200:203], v[30:33]
	v_mfma_f32_16x16x32_bf16 v[26:29], v[138:141], v[200:203], v[26:29]
	v_mfma_f32_16x16x32_bf16 v[18:21], v[130:133], v[208:211], v[18:21]
	v_mfma_f32_16x16x32_bf16 v[10:13], v[138:141], v[208:211], v[10:13]
	v_mfma_f32_16x16x32_bf16 v[62:65], v[134:137], v[166:169], v[62:65]
	v_mfma_f32_16x16x32_bf16 v[58:61], v[142:145], v[166:169], v[58:61]
	v_mfma_f32_16x16x32_bf16 v[50:53], v[134:137], v[174:177], v[50:53]
	v_mfma_f32_16x16x32_bf16 v[42:45], v[142:145], v[174:177], v[42:45]
	v_mfma_f32_16x16x32_bf16 v[30:33], v[134:137], v[204:207], v[30:33]
	v_mfma_f32_16x16x32_bf16 v[26:29], v[142:145], v[204:207], v[26:29]
	v_mfma_f32_16x16x32_bf16 v[18:21], v[134:137], v[212:215], v[18:21]
	v_mfma_f32_16x16x32_bf16 v[10:13], v[142:145], v[212:215], v[10:13]
	s_setprio 0
	s_setprio 1
	v_mfma_f32_16x16x32_bf16 v[54:57], v[146:149], v[162:165], v[54:57]
	v_mfma_f32_16x16x32_bf16 v[46:49], v[154:157], v[162:165], v[46:49]
	v_mfma_f32_16x16x32_bf16 v[38:41], v[146:149], v[170:173], v[38:41]
	v_mfma_f32_16x16x32_bf16 v[34:37], v[154:157], v[170:173], v[34:37]
	v_mfma_f32_16x16x32_bf16 v[22:25], v[146:149], v[200:203], v[22:25]
	v_mfma_f32_16x16x32_bf16 v[14:17], v[154:157], v[200:203], v[14:17]
	v_mfma_f32_16x16x32_bf16 v[6:9], v[146:149], v[208:211], v[6:9]
	v_mfma_f32_16x16x32_bf16 v[2:5], v[154:157], v[208:211], v[2:5]
	v_mfma_f32_16x16x32_bf16 v[54:57], v[150:153], v[166:169], v[54:57]
	v_mfma_f32_16x16x32_bf16 v[46:49], v[158:161], v[166:169], v[46:49]
	v_mfma_f32_16x16x32_bf16 v[38:41], v[150:153], v[174:177], v[38:41]
	v_mfma_f32_16x16x32_bf16 v[34:37], v[158:161], v[174:177], v[34:37]
	v_mfma_f32_16x16x32_bf16 v[22:25], v[150:153], v[204:207], v[22:25]
	v_mfma_f32_16x16x32_bf16 v[14:17], v[158:161], v[204:207], v[14:17]
	v_mfma_f32_16x16x32_bf16 v[6:9], v[150:153], v[212:215], v[6:9]
	v_mfma_f32_16x16x32_bf16 v[2:5], v[158:161], v[212:215], v[2:5]
	s_setprio 0
	s_barrier
	s_add_i32 s52, s52, 2
	s_add_u32 s24, s24, 0x100
	s_addc_u32 s25, s25, 0
	s_add_u32 s17, s17, 0x100
	s_addc_u32 s40, s40, 0
	s_cmp_gt_u32 s52, 29
	s_cbranch_scc0 .LBB0_2035
	s_cmp_ge_u32 s74, 16
	s_cbranch_scc1 .Lwpf_c
	s_lshl_b32 s100, s74, 9
	v_add_u32_e32 v130, s100, v246
	v_lshrrev_b32_e32 v131, 2, v130
	v_and_b32_e32 v130, 3, v130
	v_lshlrev_b32_e32 v130, 7, v130
	v_lshl_add_u32 v130, v131, 12, v130
	s_add_u32 s100, s88, 0x1800000
	s_addc_u32 s101, s89, 0
	s_mov_b32 m0, 0x21000
	s_nop 0
	global_load_lds_dword v130, s[100:101]

; #define PG8_STAGE(bufoff, gbase, voff) do { _Pragma("unroll") for (int _i = 0; _i < 2; ++_i) \
;         __builtin_amdgcn_global_load_lds((const unsigned*)((const char*)(gbase) + (voff)[_i]), (LAS unsigned*)(lds + (bufoff) + ldsw + _i * 8192), 16, 0, 0); } while (0)
; #define PG8_LDA(dst, b, h) do { _Pragma("unroll") for (int m = 0; m < 4; ++m) _Pragma("unroll") for (int k = 0; k < 2; ++k) dst[m][k] = *(const LAS bf16x8*)(lds + PG8_SA(b, h) + aoff + m * 2048 + k * 1024); } while (0)
; #define PG8_LDB(dst, b, h) do { _Pragma("unroll") for (int n = 0; n < 2; ++n) _Pragma("unroll") for (int k = 0; k < 2; ++k) dst[n][k] = *(const LAS bf16x8*)(lds + PG8_SB(b, h) + boff + n * 2048 + k * 1024); } while (0)
; #define PG8_MMA(ai, bj, At, Bt) do { __builtin_amdgcn_s_setprio(1); _Pragma("unroll") for (int m = 0; m < 4; ++m) _Pragma("unroll") for (int n = 0; n < 2; ++n) _Pragma("unroll") for (int k = 0; k < 2; ++k) \
;         acc[ai][bj][m][n] = __builtin_amdgcn_mfma_f32_16x16x32_bf16(Bt[n][k], At[m][k], acc[ai][bj][m][n], 0, 0, 0); __builtin_amdgcn_s_setprio(0); } while (0)
; #define PG8_WAIT_V(n) asm volatile("s_waitcnt vmcnt(" #n ")" ::: "memory")
; #define PG8_WAIT_L(n) asm volatile("s_waitcnt lgkmcnt(" #n ")" ::: "memory")
; #define PG8_BAR __builtin_amdgcn_s_barrier()
; #define PG8_SCHED __builtin_amdgcn_sched_barrier(0)
; template <class Epi>
; __device__ __forceinline__ void gemm_phase(LAS unsigned char* lds, const Gemm g, const StaticOrder& S, const Epi& E) {
;     ...
;             const bool last = (t == nt - 2);
;             const char* a1 = cA + (size_t)(t + 1) * kstep;
;             const char* a2 = last ? nA : cA + (size_t)(t + 2) * kstep; const char* b2 = last ? nB : cB + (size_t)(t + 2) * kstep;
;             const char* a3 = a2 + kstep; const char* b3 = b2 + kstep;
;             PG8_LDB(B0, 0, 0); PG8_LDB(B1, 0, 1); PG8_SCHED; PG8_LDA(At, 0, 0); PG8_STAGE(PG8_SA(1, 1), a1 + hstepA, voffA);
;             PG8_WAIT_V(8); PG8_WAIT_L(0); PG8_BAR; PG8_MMA(0, 0, At, B0); PG8_MMA(0, 1, At, B1); PG8_BAR; PG8_SCHED;
;             PG8_LDA(At, 0, 1); PG8_STAGE(PG8_SB(0, 0), b2, voffB); PG8_STAGE(PG8_SB(0, 1), b2 + hstepB, voffB); PG8_STAGE(PG8_SA(0, 0), a2, voffA);
;             PG8_WAIT_V(8); PG8_WAIT_L(0); PG8_BAR; PG8_MMA(1, 0, At, B0); PG8_MMA(1, 1, At, B1); PG8_BAR; PG8_SCHED;
.LBB0_2130:
	s_add_u32 s14, s20, 0xfff80080
	s_addc_u32 s15, s21, -1
	s_add_i32 s62, 0, 0x10000
	s_cmp_eq_u32 s41, 28
	s_cselect_b32 s23, s3, s15
	s_cselect_b32 s22, s11, s14
	v_add_u32_e32 v142, s62, v1
	s_cselect_b32 s15, s9, s53
	s_cselect_b32 s14, s40, s52
	s_add_i32 s64, 0, 0x14000
	ds_read_b128 v[146:149], v142
	ds_read_b128 v[150:153], v142 offset:1024
	ds_read_b128 v[154:157], v142 offset:2048
	ds_read_b128 v[158:161], v142 offset:3072
	v_add_u32_e32 v142, s64, v1
	ds_read_b128 v[162:165], v142
	ds_read_b128 v[166:169], v142 offset:1024
	ds_read_b128 v[170:173], v142 offset:2048
	ds_read_b128 v[174:177], v142 offset:3072
	v_lshl_add_u64 v[142:143], s[20:21], 0, v[138:139]
	s_add_i32 m0, s19, 0xc000
	ds_read_b128 v[188:191], v144
	ds_read_b128 v[192:195], v144 offset:1024
	ds_read_b128 v[196:199], v144 offset:2048
	ds_read_b128 v[200:203], v144 offset:3072
	ds_read_b128 v[204:207], v144 offset:4096
	ds_read_b128 v[208:211], v144 offset:5120
	ds_read_b128 v[212:215], v144 offset:6144
	ds_read_b128 v[216:219], v144 offset:7168
	global_load_lds_dwordx4 v[142:143], off
	v_lshl_add_u64 v[142:143], s[20:21], 0, v[140:141]
	s_add_i32 m0, s19, 0xe000
	s_nop 0
	global_load_lds_dwordx4 v[142:143], off
	s_waitcnt vmcnt(8)
	s_waitcnt lgkmcnt(0)
	s_barrier
	s_setprio 1
	s_waitcnt lgkmcnt(0)
	v_mfma_f32_16x16x32_bf16 v[126:129], v[146:149], v[188:191], v[126:129]
	v_mfma_f32_16x16x32_bf16 v[122:125], v[154:157], v[188:191], v[122:125]
	v_mfma_f32_16x16x32_bf16 v[110:113], v[146:149], v[196:199], v[110:113]
	v_mfma_f32_16x16x32_bf16 v[106:109], v[154:157], v[196:199], v[106:109]
	v_mfma_f32_16x16x32_bf16 v[94:97], v[146:149], v[204:207], v[94:97]
	v_mfma_f32_16x16x32_bf16 v[90:93], v[154:157], v[204:207], v[90:93]
	v_mfma_f32_16x16x32_bf16 v[78:81], v[146:149], v[212:215], v[78:81]
	v_mfma_f32_16x16x32_bf16 v[74:77], v[154:157], v[212:215], v[74:77]
	v_mfma_f32_16x16x32_bf16 v[126:129], v[150:153], v[192:195], v[126:129]
	v_mfma_f32_16x16x32_bf16 v[122:125], v[158:161], v[192:195], v[122:125]
	v_mfma_f32_16x16x32_bf16 v[110:113], v[150:153], v[200:203], v[110:113]
	v_mfma_f32_16x16x32_bf16 v[106:109], v[158:161], v[200:203], v[106:109]
	v_mfma_f32_16x16x32_bf16 v[94:97], v[150:153], v[208:211], v[94:97]
	v_mfma_f32_16x16x32_bf16 v[90:93], v[158:161], v[208:211], v[90:93]
	v_mfma_f32_16x16x32_bf16 v[78:81], v[150:153], v[216:219], v[78:81]
	v_mfma_f32_16x16x32_bf16 v[74:77], v[158:161], v[216:219], v[74:77]
	s_setprio 0
	s_setprio 1
	v_mfma_f32_16x16x32_bf16 v[118:121], v[162:165], v[188:191], v[118:121]
	v_mfma_f32_16x16x32_bf16 v[114:117], v[170:173], v[188:191], v[114:117]
	v_mfma_f32_16x16x32_bf16 v[102:105], v[162:165], v[196:199], v[102:105]
	v_mfma_f32_16x16x32_bf16 v[98:101], v[170:173], v[196:199], v[98:101]
	v_mfma_f32_16x16x32_bf16 v[86:89], v[162:165], v[204:207], v[86:89]
	v_mfma_f32_16x16x32_bf16 v[82:85], v[170:173], v[204:207], v[82:85]
	v_mfma_f32_16x16x32_bf16 v[70:73], v[162:165], v[212:215], v[70:73]
	v_mfma_f32_16x16x32_bf16 v[66:69], v[170:173], v[212:215], v[66:69]
	v_mfma_f32_16x16x32_bf16 v[118:121], v[166:169], v[192:195], v[118:121]
	v_mfma_f32_16x16x32_bf16 v[114:117], v[174:177], v[192:195], v[114:117]
	v_mfma_f32_16x16x32_bf16 v[102:105], v[166:169], v[200:203], v[102:105]
	v_mfma_f32_16x16x32_bf16 v[98:101], v[174:177], v[200:203], v[98:101]
	v_mfma_f32_16x16x32_bf16 v[86:89], v[166:169], v[208:211], v[86:89]
	v_mfma_f32_16x16x32_bf16 v[82:85], v[174:177], v[208:211], v[82:85]
	v_mfma_f32_16x16x32_bf16 v[70:73], v[166:169], v[216:219], v[70:73]
	v_mfma_f32_16x16x32_bf16 v[66:69], v[174:177], v[216:219], v[66:69]
	s_setprio 0
	s_barrier
	s_add_i32 s62, s62, s27
	v_lshl_add_u64 v[142:143], s[14:15], 0, v[132:133]
	s_mov_b32 m0, s62
	ds_read_b128 v[188:191], v144 offset:16384
	ds_read_b128 v[192:195], v144 offset:17408
	ds_read_b128 v[196:199], v144 offset:18432
	ds_read_b128 v[200:203], v144 offset:19456
	ds_read_b128 v[204:207], v144 offset:20480
	ds_read_b128 v[208:211], v144 offset:21504
	ds_read_b128 v[212:215], v144 offset:22528
	ds_read_b128 v[216:219], v144 offset:23552
	global_load_lds_dwordx4 v[142:143], off
	s_add_i32 m0, s62, 0x2000
	s_add_u32 s62, s14, 0x80000
	v_lshl_add_u64 v[178:179], s[14:15], 0, v[136:137]
	s_addc_u32 s63, s15, 0
	s_add_i32 s64, s64, s27
	global_load_lds_dwordx4 v[178:179], off
	v_lshl_add_u64 v[184:185], s[62:63], 0, v[132:133]
	s_mov_b32 m0, s64
	v_lshl_add_u64 v[220:221], s[22:23], 0, v[134:135]
	global_load_lds_dwordx4 v[184:185], off
	v_lshl_add_u64 v[184:185], s[62:63], 0, v[136:137]
	s_add_i32 m0, s64, 0x2000
	s_nop 0
	global_load_lds_dwordx4 v[184:185], off
	v_lshl_add_u64 v[184:185], s[22:23], 0, v[130:131]
	s_mov_b32 m0, s19
	s_nop 0
	global_load_lds_dwordx4 v[184:185], off
	s_mov_b32 m0, s28
	s_nop 0
	global_load_lds_dwordx4 v[220:221], off
	s_waitcnt vmcnt(8)
	s_waitcnt lgkmcnt(0)
	s_barrier
; #define PG8_STAGE(bufoff, gbase, voff) do { _Pragma("unroll") for (int _i = 0; _i < 2; ++_i) \
;         __builtin_amdgcn_global_load_lds((const unsigned*)((const char*)(gbase) + (voff)[_i]), (LAS unsigned*)(lds + (bufoff) + ldsw + _i * 8192), 16, 0, 0); } while (0)
; #define PG8_LDA(dst, b, h) do { _Pragma("unroll") for (int m = 0; m < 4; ++m) _Pragma("unroll") for (int k = 0; k < 2; ++k) dst[m][k] = *(const LAS bf16x8*)(lds + PG8_SA(b, h) + aoff + m * 2048 + k * 1024); } while (0)
; #define PG8_LDB(dst, b, h) do { _Pragma("unroll") for (int n = 0; n < 2; ++n) _Pragma("unroll") for (int k = 0; k < 2; ++k) dst[n][k] = *(const LAS bf16x8*)(lds + PG8_SB(b, h) + boff + n * 2048 + k * 1024); } while (0)
; #define PG8_MMA(ai, bj, At, Bt) do { __builtin_amdgcn_s_setprio(1); _Pragma("unroll") for (int m = 0; m < 4; ++m) _Pragma("unroll") for (int n = 0; n < 2; ++n) _Pragma("unroll") for (int k = 0; k < 2; ++k) \
;         acc[ai][bj][m][n] = __builtin_amdgcn_mfma_f32_16x16x32_bf16(Bt[n][k], At[m][k], acc[ai][bj][m][n], 0, 0, 0); __builtin_amdgcn_s_setprio(0); } while (0)
; #define PG8_WAIT_V(n) asm volatile("s_waitcnt vmcnt(" #n ")" ::: "memory")
; #define PG8_WAIT_L(n) asm volatile("s_waitcnt lgkmcnt(" #n ")" ::: "memory")
; #define PG8_BAR __builtin_amdgcn_s_barrier()
; #define PG8_SCHED __builtin_amdgcn_sched_barrier(0)
; template <class Epi>
; __device__ __forceinline__ void gemm_phase(LAS unsigned char* lds, const Gemm g, const StaticOrder& S, const Epi& E) {
;     ...
;             PG8_WAIT_V(8); PG8_WAIT_L(0); PG8_BAR; PG8_MMA(1, 0, At, B0); PG8_MMA(1, 1, At, B1); PG8_BAR; PG8_SCHED;
;             PG8_LDB(B0, 1, 0); PG8_LDB(B1, 1, 1); PG8_SCHED; PG8_LDA(At, 1, 0); PG8_STAGE(PG8_SA(0, 1), a2 + hstepA, voffA);
;             PG8_WAIT_V(8); PG8_WAIT_L(0); PG8_BAR; PG8_MMA(0, 0, At, B0); PG8_MMA(0, 1, At, B1); PG8_BAR; PG8_SCHED;
;             PG8_LDA(At, 1, 1); PG8_STAGE(PG8_SB(1, 0), b3, voffB); PG8_STAGE(PG8_SB(1, 1), b3 + hstepB, voffB); PG8_STAGE(PG8_SA(1, 0), a3, voffA);
;             PG8_WAIT_V(8); PG8_WAIT_L(0); PG8_BAR; PG8_MMA(1, 0, At, B0); PG8_MMA(1, 1, At, B1); PG8_BAR; PG8_SCHED;
	s_setprio 1
	s_waitcnt lgkmcnt(0)
	v_mfma_f32_16x16x32_bf16 v[62:65], v[146:149], v[188:191], v[62:65]
	v_mfma_f32_16x16x32_bf16 v[58:61], v[154:157], v[188:191], v[58:61]
	v_mfma_f32_16x16x32_bf16 v[46:49], v[146:149], v[196:199], v[46:49]
	v_mfma_f32_16x16x32_bf16 v[42:45], v[154:157], v[196:199], v[42:45]
	v_mfma_f32_16x16x32_bf16 v[30:33], v[146:149], v[204:207], v[30:33]
	v_mfma_f32_16x16x32_bf16 v[26:29], v[154:157], v[204:207], v[26:29]
	v_mfma_f32_16x16x32_bf16 v[14:17], v[146:149], v[212:215], v[14:17]
	v_mfma_f32_16x16x32_bf16 v[10:13], v[154:157], v[212:215], v[10:13]
	v_mfma_f32_16x16x32_bf16 v[62:65], v[150:153], v[192:195], v[62:65]
	v_mfma_f32_16x16x32_bf16 v[58:61], v[158:161], v[192:195], v[58:61]
	v_mfma_f32_16x16x32_bf16 v[46:49], v[150:153], v[200:203], v[46:49]
	v_mfma_f32_16x16x32_bf16 v[42:45], v[158:161], v[200:203], v[42:45]
	v_mfma_f32_16x16x32_bf16 v[30:33], v[150:153], v[208:211], v[30:33]
	v_mfma_f32_16x16x32_bf16 v[26:29], v[158:161], v[208:211], v[26:29]
	v_mfma_f32_16x16x32_bf16 v[14:17], v[150:153], v[216:219], v[14:17]
	v_mfma_f32_16x16x32_bf16 v[10:13], v[158:161], v[216:219], v[10:13]
	s_setprio 0
	s_setprio 1
	v_mfma_f32_16x16x32_bf16 v[54:57], v[162:165], v[188:191], v[54:57]
	v_mfma_f32_16x16x32_bf16 v[50:53], v[170:173], v[188:191], v[50:53]
	v_mfma_f32_16x16x32_bf16 v[38:41], v[162:165], v[196:199], v[38:41]
	v_mfma_f32_16x16x32_bf16 v[34:37], v[170:173], v[196:199], v[34:37]
	v_mfma_f32_16x16x32_bf16 v[22:25], v[162:165], v[204:207], v[22:25]
	v_mfma_f32_16x16x32_bf16 v[18:21], v[170:173], v[204:207], v[18:21]
	v_mfma_f32_16x16x32_bf16 v[6:9], v[162:165], v[212:215], v[6:9]
	v_mfma_f32_16x16x32_bf16 v[2:5], v[170:173], v[212:215], v[2:5]
	v_mfma_f32_16x16x32_bf16 v[54:57], v[166:169], v[192:195], v[54:57]
	v_mfma_f32_16x16x32_bf16 v[50:53], v[174:177], v[192:195], v[50:53]
	v_mfma_f32_16x16x32_bf16 v[38:41], v[166:169], v[200:203], v[38:41]
	v_mfma_f32_16x16x32_bf16 v[34:37], v[174:177], v[200:203], v[34:37]
	v_mfma_f32_16x16x32_bf16 v[22:25], v[166:169], v[208:211], v[22:25]
	v_mfma_f32_16x16x32_bf16 v[18:21], v[174:177], v[208:211], v[18:21]
	v_mfma_f32_16x16x32_bf16 v[6:9], v[166:169], v[216:219], v[6:9]
	v_mfma_f32_16x16x32_bf16 v[2:5], v[174:177], v[216:219], v[2:5]
	s_setprio 0
	s_barrier
	s_add_i32 s62, 0, 0x18000
	v_add_u32_e32 v145, s62, v1
	s_add_i32 s63, 0, 0x1c000
	ds_read_b128 v[146:149], v145
	ds_read_b128 v[150:153], v145 offset:1024
	ds_read_b128 v[154:157], v145 offset:2048
	ds_read_b128 v[158:161], v145 offset:3072
	v_add_u32_e32 v145, s63, v1
	ds_read_b128 v[162:165], v145
	ds_read_b128 v[166:169], v145 offset:1024
	ds_read_b128 v[170:173], v145 offset:2048
	ds_read_b128 v[174:177], v145 offset:3072
	s_add_u32 s22, s22, 0x80000
	s_addc_u32 s23, s23, 0
	s_mov_b32 m0, s29
	v_lshl_add_u64 v[222:223], s[22:23], 0, v[130:131]
	ds_read_b128 v[188:191], v144 offset:32768
	ds_read_b128 v[192:195], v144 offset:33792
	ds_read_b128 v[196:199], v144 offset:34816
	ds_read_b128 v[200:203], v144 offset:35840
	ds_read_b128 v[204:207], v144 offset:36864
	ds_read_b128 v[208:211], v144 offset:37888
	ds_read_b128 v[212:215], v144 offset:38912
	ds_read_b128 v[216:219], v144 offset:39936
	global_load_lds_dwordx4 v[222:223], off
	v_lshl_add_u64 v[222:223], s[22:23], 0, v[134:135]
	s_mov_b32 m0, s30
	s_nop 0
	global_load_lds_dwordx4 v[222:223], off
	s_waitcnt vmcnt(8)
	s_waitcnt lgkmcnt(0)
	s_barrier
	s_setprio 1
	s_waitcnt lgkmcnt(0)
	v_mfma_f32_16x16x32_bf16 v[126:129], v[146:149], v[188:191], v[126:129]
	v_mfma_f32_16x16x32_bf16 v[122:125], v[154:157], v[188:191], v[122:125]
	v_mfma_f32_16x16x32_bf16 v[110:113], v[146:149], v[196:199], v[110:113]
	v_mfma_f32_16x16x32_bf16 v[106:109], v[154:157], v[196:199], v[106:109]
	v_mfma_f32_16x16x32_bf16 v[94:97], v[146:149], v[204:207], v[94:97]
	v_mfma_f32_16x16x32_bf16 v[90:93], v[154:157], v[204:207], v[90:93]
	v_mfma_f32_16x16x32_bf16 v[78:81], v[146:149], v[212:215], v[78:81]
	v_mfma_f32_16x16x32_bf16 v[74:77], v[154:157], v[212:215], v[74:77]
	v_mfma_f32_16x16x32_bf16 v[126:129], v[150:153], v[192:195], v[126:129]
	v_mfma_f32_16x16x32_bf16 v[122:125], v[158:161], v[192:195], v[122:125]
	v_mfma_f32_16x16x32_bf16 v[110:113], v[150:153], v[200:203], v[110:113]
	v_mfma_f32_16x16x32_bf16 v[106:109], v[158:161], v[200:203], v[106:109]
	v_mfma_f32_16x16x32_bf16 v[94:97], v[150:153], v[208:211], v[94:97]
	v_mfma_f32_16x16x32_bf16 v[90:93], v[158:161], v[208:211], v[90:93]
	v_mfma_f32_16x16x32_bf16 v[78:81], v[150:153], v[216:219], v[78:81]
	v_mfma_f32_16x16x32_bf16 v[74:77], v[158:161], v[216:219], v[74:77]
	s_setprio 0
	s_setprio 1
	v_mfma_f32_16x16x32_bf16 v[118:121], v[162:165], v[188:191], v[118:121]
	v_mfma_f32_16x16x32_bf16 v[114:117], v[170:173], v[188:191], v[114:117]
	v_mfma_f32_16x16x32_bf16 v[102:105], v[162:165], v[196:199], v[102:105]
	v_mfma_f32_16x16x32_bf16 v[98:101], v[170:173], v[196:199], v[98:101]
	v_mfma_f32_16x16x32_bf16 v[86:89], v[162:165], v[204:207], v[86:89]
	v_mfma_f32_16x16x32_bf16 v[82:85], v[170:173], v[204:207], v[82:85]
	v_mfma_f32_16x16x32_bf16 v[70:73], v[162:165], v[212:215], v[70:73]
	v_mfma_f32_16x16x32_bf16 v[66:69], v[170:173], v[212:215], v[66:69]
	v_mfma_f32_16x16x32_bf16 v[118:121], v[166:169], v[192:195], v[118:121]
	v_mfma_f32_16x16x32_bf16 v[114:117], v[174:177], v[192:195], v[114:117]
	v_mfma_f32_16x16x32_bf16 v[102:105], v[166:169], v[200:203], v[102:105]
	v_mfma_f32_16x16x32_bf16 v[98:101], v[174:177], v[200:203], v[98:101]
	v_mfma_f32_16x16x32_bf16 v[86:89], v[166:169], v[208:211], v[86:89]
	v_mfma_f32_16x16x32_bf16 v[82:85], v[174:177], v[208:211], v[82:85]
	v_mfma_f32_16x16x32_bf16 v[70:73], v[166:169], v[216:219], v[70:73]
	v_mfma_f32_16x16x32_bf16 v[66:69], v[174:177], v[216:219], v[66:69]
	s_setprio 0
	s_barrier
; #define PG8_STAGE(bufoff, gbase, voff) do { _Pragma("unroll") for (int _i = 0; _i < 2; ++_i) \
;         __builtin_amdgcn_global_load_lds((const unsigned*)((const char*)(gbase) + (voff)[_i]), (LAS unsigned*)(lds + (bufoff) + ldsw + _i * 8192), 16, 0, 0); } while (0)
; #define PG8_LDA(dst, b, h) do { _Pragma("unroll") for (int m = 0; m < 4; ++m) _Pragma("unroll") for (int k = 0; k < 2; ++k) dst[m][k] = *(const LAS bf16x8*)(lds + PG8_SA(b, h) + aoff + m * 2048 + k * 1024); } while (0)
; #define PG8_MMA(ai, bj, At, Bt) do { __builtin_amdgcn_s_setprio(1); _Pragma("unroll") for (int m = 0; m < 4; ++m) _Pragma("unroll") for (int n = 0; n < 2; ++n) _Pragma("unroll") for (int k = 0; k < 2; ++k) \
;         acc[ai][bj][m][n] = __builtin_amdgcn_mfma_f32_16x16x32_bf16(Bt[n][k], At[m][k], acc[ai][bj][m][n], 0, 0, 0); __builtin_amdgcn_s_setprio(0); } while (0)
; #define PG8_WAIT_V(n) asm volatile("s_waitcnt vmcnt(" #n ")" ::: "memory")
; #define PG8_WAIT_L(n) asm volatile("s_waitcnt lgkmcnt(" #n ")" ::: "memory")
; #define PG8_BAR __builtin_amdgcn_s_barrier()
; #define PG8_SCHED __builtin_amdgcn_sched_barrier(0)
; template <class Epi>
; __device__ __forceinline__ void gemm_phase(LAS unsigned char* lds, const Gemm g, const StaticOrder& S, const Epi& E) {
;     ...
;             PG8_LDA(At, 1, 1); PG8_STAGE(PG8_SB(1, 0), b3, voffB); PG8_STAGE(PG8_SB(1, 1), b3 + hstepB, voffB); PG8_STAGE(PG8_SA(1, 0), a3, voffA);
;             PG8_WAIT_V(8); PG8_WAIT_L(0); PG8_BAR; PG8_MMA(1, 0, At, B0); PG8_MMA(1, 1, At, B1); PG8_BAR; PG8_SCHED;
;         }
;         if (wr == 0) PG8_BAR;
	s_add_i32 s22, s62, s27
	v_lshl_add_u64 v[142:143], v[142:143], 0, s[84:85]
	s_mov_b32 m0, s22
	ds_read_b128 v[188:191], v144 offset:49152
	ds_read_b128 v[192:195], v144 offset:50176
	ds_read_b128 v[196:199], v144 offset:51200
	ds_read_b128 v[200:203], v144 offset:52224
	ds_read_b128 v[204:207], v144 offset:53248
	ds_read_b128 v[208:211], v144 offset:54272
	ds_read_b128 v[212:215], v144 offset:55296
	ds_read_b128 v[216:219], v144 offset:56320
	global_load_lds_dwordx4 v[142:143], off
	s_add_i32 m0, s22, 0x2000
	s_add_u32 s14, s14, 0x80080
	v_lshl_add_u64 v[142:143], v[178:179], 0, s[84:85]
	s_addc_u32 s15, s15, 0
	s_add_i32 s22, s63, s27
	global_load_lds_dwordx4 v[142:143], off
	v_lshl_add_u64 v[142:143], s[14:15], 0, v[132:133]
	s_mov_b32 m0, s22
	s_nop 0
	global_load_lds_dwordx4 v[142:143], off
	v_lshl_add_u64 v[142:143], s[14:15], 0, v[136:137]
	s_add_i32 m0, s22, 0x2000
	s_nop 0
	global_load_lds_dwordx4 v[142:143], off
	v_lshl_add_u64 v[142:143], v[184:185], 0, s[84:85]
	s_mov_b32 m0, s34
	s_nop 0
	global_load_lds_dwordx4 v[142:143], off
	v_lshl_add_u64 v[142:143], v[220:221], 0, s[84:85]
	s_mov_b32 m0, s35
	s_nop 0
	global_load_lds_dwordx4 v[142:143], off
	s_waitcnt vmcnt(8)
	s_waitcnt lgkmcnt(0)
	s_barrier
	s_setprio 1
	s_waitcnt lgkmcnt(0)
	v_mfma_f32_16x16x32_bf16 v[62:65], v[146:149], v[188:191], v[62:65]
	v_mfma_f32_16x16x32_bf16 v[58:61], v[154:157], v[188:191], v[58:61]
	v_mfma_f32_16x16x32_bf16 v[46:49], v[146:149], v[196:199], v[46:49]
	v_mfma_f32_16x16x32_bf16 v[42:45], v[154:157], v[196:199], v[42:45]
	v_mfma_f32_16x16x32_bf16 v[30:33], v[146:149], v[204:207], v[30:33]
	v_mfma_f32_16x16x32_bf16 v[26:29], v[154:157], v[204:207], v[26:29]
	v_mfma_f32_16x16x32_bf16 v[14:17], v[146:149], v[212:215], v[14:17]
	v_mfma_f32_16x16x32_bf16 v[10:13], v[154:157], v[212:215], v[10:13]
	v_mfma_f32_16x16x32_bf16 v[62:65], v[150:153], v[192:195], v[62:65]
	v_mfma_f32_16x16x32_bf16 v[58:61], v[158:161], v[192:195], v[58:61]
	v_mfma_f32_16x16x32_bf16 v[46:49], v[150:153], v[200:203], v[46:49]
	v_mfma_f32_16x16x32_bf16 v[42:45], v[158:161], v[200:203], v[42:45]
	v_mfma_f32_16x16x32_bf16 v[30:33], v[150:153], v[208:211], v[30:33]
	v_mfma_f32_16x16x32_bf16 v[26:29], v[158:161], v[208:211], v[26:29]
	v_mfma_f32_16x16x32_bf16 v[14:17], v[150:153], v[216:219], v[14:17]
	v_mfma_f32_16x16x32_bf16 v[10:13], v[158:161], v[216:219], v[10:13]
	s_setprio 0
	s_setprio 1
	v_mfma_f32_16x16x32_bf16 v[54:57], v[162:165], v[188:191], v[54:57]
	v_mfma_f32_16x16x32_bf16 v[50:53], v[170:173], v[188:191], v[50:53]
	v_mfma_f32_16x16x32_bf16 v[38:41], v[162:165], v[196:199], v[38:41]
	v_mfma_f32_16x16x32_bf16 v[34:37], v[170:173], v[196:199], v[34:37]
	v_mfma_f32_16x16x32_bf16 v[22:25], v[162:165], v[204:207], v[22:25]
	v_mfma_f32_16x16x32_bf16 v[18:21], v[170:173], v[204:207], v[18:21]
	v_mfma_f32_16x16x32_bf16 v[6:9], v[162:165], v[212:215], v[6:9]
	v_mfma_f32_16x16x32_bf16 v[2:5], v[170:173], v[212:215], v[2:5]
	v_mfma_f32_16x16x32_bf16 v[54:57], v[166:169], v[192:195], v[54:57]
	v_mfma_f32_16x16x32_bf16 v[50:53], v[174:177], v[192:195], v[50:53]
	v_mfma_f32_16x16x32_bf16 v[38:41], v[166:169], v[200:203], v[38:41]
	v_mfma_f32_16x16x32_bf16 v[34:37], v[174:177], v[200:203], v[34:37]
	v_mfma_f32_16x16x32_bf16 v[22:25], v[166:169], v[208:211], v[22:25]
	v_mfma_f32_16x16x32_bf16 v[18:21], v[174:177], v[208:211], v[18:21]
	v_mfma_f32_16x16x32_bf16 v[6:9], v[166:169], v[216:219], v[6:9]
	v_mfma_f32_16x16x32_bf16 v[2:5], v[174:177], v[216:219], v[2:5]
	s_setprio 0
	s_barrier
	s_add_i32 s41, s41, 2
	s_add_u32 s20, s20, 0x100
	s_addc_u32 s21, s21, 0
	s_add_u32 s52, s52, 0x100
	s_addc_u32 s53, s53, 0
	s_cmp_gt_u32 s41, 29
	s_cbranch_scc0 .LBB0_2130
	s_cmp_ge_u32 s74, 16
	s_cbranch_scc1 .Lwpf_d
	s_lshl_b32 s100, s74, 9
	v_add_u32_e32 v146, s100, v246
	v_lshrrev_b32_e32 v147, 2, v146
	v_and_b32_e32 v146, 3, v146
	v_lshlrev_b32_e32 v146, 7, v146
	v_lshl_add_u32 v146, v147, 14, v146
	s_add_u32 s100, s88, 0x2000000
	s_addc_u32 s101, s89, 0
	s_mov_b32 m0, 0x21000
	s_nop 0
	global_load_lds_dword v146, s[100:101]
.Lwpf_d:
	s_and_b64 vcc, exec, s[6:7]
	s_cbranch_vccz .LBB0_2133
	s_barrier

; #define PG8_STAGE(bufoff, gbase, voff) do { _Pragma("unroll") for (int _i = 0; _i < 2; ++_i) \
;         __builtin_amdgcn_global_load_lds((const unsigned*)((const char*)(gbase) + (voff)[_i]), (LAS unsigned*)(lds + (bufoff) + ldsw + _i * 8192), 16, 0, 0); } while (0)
; #define PG8_LDA(dst, b, h) do { _Pragma("unroll") for (int m = 0; m < 4; ++m) _Pragma("unroll") for (int k = 0; k < 2; ++k) dst[m][k] = *(const LAS bf16x8*)(lds + PG8_SA(b, h) + aoff + m * 2048 + k * 1024); } while (0)
; #define PG8_LDB(dst, b, h) do { _Pragma("unroll") for (int n = 0; n < 2; ++n) _Pragma("unroll") for (int k = 0; k < 2; ++k) dst[n][k] = *(const LAS bf16x8*)(lds + PG8_SB(b, h) + boff + n * 2048 + k * 1024); } while (0)
; #define PG8_MMA(ai, bj, At, Bt) do { __builtin_amdgcn_s_setprio(1); _Pragma("unroll") for (int m = 0; m < 4; ++m) _Pragma("unroll") for (int n = 0; n < 2; ++n) _Pragma("unroll") for (int k = 0; k < 2; ++k) \
;         acc[ai][bj][m][n] = __builtin_amdgcn_mfma_f32_16x16x32_bf16(Bt[n][k], At[m][k], acc[ai][bj][m][n], 0, 0, 0); __builtin_amdgcn_s_setprio(0); } while (0)
; #define PG8_WAIT_V(n) asm volatile("s_waitcnt vmcnt(" #n ")" ::: "memory")
; #define PG8_WAIT_L(n) asm volatile("s_waitcnt lgkmcnt(" #n ")" ::: "memory")
; #define PG8_BAR __builtin_amdgcn_s_barrier()
; #define PG8_SCHED __builtin_amdgcn_sched_barrier(0)
; template <class Epi>
; __device__ __forceinline__ void gemm_phase(LAS unsigned char* lds, const Gemm g, const StaticOrder& S, const Epi& E) {
;     ...
;             const bool last = (t == nt - 2);
;             const char* a1 = cA + (size_t)(t + 1) * kstep;
;             const char* a2 = last ? nA : cA + (size_t)(t + 2) * kstep; const char* b2 = last ? nB : cB + (size_t)(t + 2) * kstep;
;             const char* a3 = a2 + kstep; const char* b3 = b2 + kstep;
;             PG8_LDB(B0, 0, 0); PG8_LDB(B1, 0, 1); PG8_SCHED; PG8_LDA(At, 0, 0); PG8_STAGE(PG8_SA(1, 1), a1 + hstepA, voffA);
;             PG8_WAIT_V(8); PG8_WAIT_L(0); PG8_BAR; PG8_MMA(0, 0, At, B0); PG8_MMA(0, 1, At, B1); PG8_BAR; PG8_SCHED;
;             PG8_LDA(At, 0, 1); PG8_STAGE(PG8_SB(0, 0), b2, voffB); PG8_STAGE(PG8_SB(0, 1), b2 + hstepB, voffB); PG8_STAGE(PG8_SA(0, 0), a2, voffA);
;             PG8_WAIT_V(8); PG8_WAIT_L(0); PG8_BAR; PG8_MMA(1, 0, At, B0); PG8_MMA(1, 1, At, B1); PG8_BAR; PG8_SCHED;
.LBB0_2233:
	s_add_u32 s14, s24, 0xffe00080
	s_addc_u32 s15, s25, -1
	s_add_i32 s52, 0, 0x10000
	s_cmpk_eq_i32 s41, 0x7c
	s_cselect_b32 s27, s1, s15
	s_cselect_b32 s26, s3, s14
	s_cselect_b32 s15, s9, s40
	s_cselect_b32 s14, s17, s19
	s_add_i32 s62, 0, 0x14000
	v_add_u32_e32 v142, s52, v1
	v_add_u32_e32 v167, s62, v1
	ds_read_b128 v[130:133], v142
	ds_read_b128 v[134:137], v142 offset:1024
	ds_read_b128 v[138:141], v142 offset:2048
	ds_read_b128 v[142:145], v142 offset:3072
	ds_read_b128 v[146:149], v167
	ds_read_b128 v[162:165], v167 offset:1024
	ds_read_b128 v[168:171], v167 offset:2048
	ds_read_b128 v[172:175], v167 offset:3072
	v_lshl_add_u64 v[184:185], s[24:25], 0, v[158:159]
	s_add_i32 m0, s31, 0xc000
	ds_read_b128 v[176:179], v166
	ds_read_b128 v[188:191], v166 offset:1024
	ds_read_b128 v[192:195], v166 offset:2048
	ds_read_b128 v[196:199], v166 offset:3072
	ds_read_b128 v[200:203], v166 offset:4096
	ds_read_b128 v[204:207], v166 offset:5120
	ds_read_b128 v[208:211], v166 offset:6144
	ds_read_b128 v[212:215], v166 offset:7168
	global_load_lds_dwordx4 v[184:185], off
	v_lshl_add_u64 v[184:185], s[24:25], 0, v[160:161]
	s_add_i32 m0, s31, 0xe000
	s_nop 0
	global_load_lds_dwordx4 v[184:185], off
	s_waitcnt vmcnt(8)
	s_waitcnt lgkmcnt(0)
	s_barrier
	s_setprio 1
	s_waitcnt lgkmcnt(0)
	v_mfma_f32_16x16x32_bf16 v[126:129], v[130:133], v[176:179], v[126:129]
	v_mfma_f32_16x16x32_bf16 v[122:125], v[138:141], v[176:179], v[122:125]
	v_mfma_f32_16x16x32_bf16 v[118:121], v[130:133], v[192:195], v[118:121]
	v_mfma_f32_16x16x32_bf16 v[114:117], v[138:141], v[192:195], v[114:117]
	v_mfma_f32_16x16x32_bf16 v[94:97], v[130:133], v[200:203], v[94:97]
	v_mfma_f32_16x16x32_bf16 v[90:93], v[138:141], v[200:203], v[90:93]
	v_mfma_f32_16x16x32_bf16 v[82:85], v[130:133], v[208:211], v[82:85]
	v_mfma_f32_16x16x32_bf16 v[74:77], v[138:141], v[208:211], v[74:77]
	v_mfma_f32_16x16x32_bf16 v[126:129], v[134:137], v[188:191], v[126:129]
	v_mfma_f32_16x16x32_bf16 v[122:125], v[142:145], v[188:191], v[122:125]
	v_mfma_f32_16x16x32_bf16 v[118:121], v[134:137], v[196:199], v[118:121]
	v_mfma_f32_16x16x32_bf16 v[114:117], v[142:145], v[196:199], v[114:117]
	v_mfma_f32_16x16x32_bf16 v[94:97], v[134:137], v[204:207], v[94:97]
	v_mfma_f32_16x16x32_bf16 v[90:93], v[142:145], v[204:207], v[90:93]
	v_mfma_f32_16x16x32_bf16 v[82:85], v[134:137], v[212:215], v[82:85]
	v_mfma_f32_16x16x32_bf16 v[74:77], v[142:145], v[212:215], v[74:77]
	s_setprio 0
	s_setprio 1
	v_mfma_f32_16x16x32_bf16 v[110:113], v[146:149], v[176:179], v[110:113]
	v_mfma_f32_16x16x32_bf16 v[106:109], v[168:171], v[176:179], v[106:109]
	v_mfma_f32_16x16x32_bf16 v[102:105], v[146:149], v[192:195], v[102:105]
	v_mfma_f32_16x16x32_bf16 v[98:101], v[168:171], v[192:195], v[98:101]
	v_mfma_f32_16x16x32_bf16 v[86:89], v[146:149], v[200:203], v[86:89]
	v_mfma_f32_16x16x32_bf16 v[78:81], v[168:171], v[200:203], v[78:81]
	v_mfma_f32_16x16x32_bf16 v[70:73], v[146:149], v[208:211], v[70:73]
	v_mfma_f32_16x16x32_bf16 v[66:69], v[168:171], v[208:211], v[66:69]
	v_mfma_f32_16x16x32_bf16 v[110:113], v[162:165], v[188:191], v[110:113]
	v_mfma_f32_16x16x32_bf16 v[106:109], v[172:175], v[188:191], v[106:109]
	v_mfma_f32_16x16x32_bf16 v[102:105], v[162:165], v[196:199], v[102:105]
	v_mfma_f32_16x16x32_bf16 v[98:101], v[172:175], v[196:199], v[98:101]
	v_mfma_f32_16x16x32_bf16 v[86:89], v[162:165], v[204:207], v[86:89]
	v_mfma_f32_16x16x32_bf16 v[78:81], v[172:175], v[204:207], v[78:81]
	v_mfma_f32_16x16x32_bf16 v[70:73], v[162:165], v[212:215], v[70:73]
	v_mfma_f32_16x16x32_bf16 v[66:69], v[172:175], v[212:215], v[66:69]
	s_setprio 0
	s_barrier
	s_add_i32 s52, s52, s30
	v_lshl_add_u64 v[184:185], s[14:15], 0, v[152:153]
	s_mov_b32 m0, s52
	ds_read_b128 v[176:179], v166 offset:16384
	ds_read_b128 v[188:191], v166 offset:17408
	ds_read_b128 v[192:195], v166 offset:18432
	ds_read_b128 v[196:199], v166 offset:19456
	ds_read_b128 v[200:203], v166 offset:20480
	ds_read_b128 v[204:207], v166 offset:21504
	ds_read_b128 v[208:211], v166 offset:22528
	ds_read_b128 v[212:215], v166 offset:23552
	global_load_lds_dwordx4 v[184:185], off
	s_add_i32 m0, s52, 0x2000
	s_add_u32 s52, s14, 0x200000
	v_lshl_add_u64 v[216:217], s[14:15], 0, v[156:157]
	s_addc_u32 s53, s15, 0
	s_add_i32 s62, s62, s30
	global_load_lds_dwordx4 v[216:217], off
	v_lshl_add_u64 v[218:219], s[52:53], 0, v[152:153]
	s_mov_b32 m0, s62
	v_lshl_add_u64 v[220:221], s[26:27], 0, v[154:155]
	global_load_lds_dwordx4 v[218:219], off
	v_lshl_add_u64 v[218:219], s[52:53], 0, v[156:157]
	s_add_i32 m0, s62, 0x2000
	s_nop 0
	global_load_lds_dwordx4 v[218:219], off
	v_lshl_add_u64 v[218:219], s[26:27], 0, v[150:151]
	s_mov_b32 m0, s31
	s_nop 0
	global_load_lds_dwordx4 v[218:219], off
	s_mov_b32 m0, s34
	s_nop 0
	global_load_lds_dwordx4 v[220:221], off
	s_waitcnt vmcnt(8)
	s_waitcnt lgkmcnt(0)
	s_barrier
; #define PG8_STAGE(bufoff, gbase, voff) do { _Pragma("unroll") for (int _i = 0; _i < 2; ++_i) \
;         __builtin_amdgcn_global_load_lds((const unsigned*)((const char*)(gbase) + (voff)[_i]), (LAS unsigned*)(lds + (bufoff) + ldsw + _i * 8192), 16, 0, 0); } while (0)
; #define PG8_LDA(dst, b, h) do { _Pragma("unroll") for (int m = 0; m < 4; ++m) _Pragma("unroll") for (int k = 0; k < 2; ++k) dst[m][k] = *(const LAS bf16x8*)(lds + PG8_SA(b, h) + aoff + m * 2048 + k * 1024); } while (0)
; #define PG8_LDB(dst, b, h) do { _Pragma("unroll") for (int n = 0; n < 2; ++n) _Pragma("unroll") for (int k = 0; k < 2; ++k) dst[n][k] = *(const LAS bf16x8*)(lds + PG8_SB(b, h) + boff + n * 2048 + k * 1024); } while (0)
; #define PG8_MMA(ai, bj, At, Bt) do { __builtin_amdgcn_s_setprio(1); _Pragma("unroll") for (int m = 0; m < 4; ++m) _Pragma("unroll") for (int n = 0; n < 2; ++n) _Pragma("unroll") for (int k = 0; k < 2; ++k) \
;         acc[ai][bj][m][n] = __builtin_amdgcn_mfma_f32_16x16x32_bf16(Bt[n][k], At[m][k], acc[ai][bj][m][n], 0, 0, 0); __builtin_amdgcn_s_setprio(0); } while (0)
; #define PG8_WAIT_V(n) asm volatile("s_waitcnt vmcnt(" #n ")" ::: "memory")
; #define PG8_WAIT_L(n) asm volatile("s_waitcnt lgkmcnt(" #n ")" ::: "memory")
; #define PG8_BAR __builtin_amdgcn_s_barrier()
; #define PG8_SCHED __builtin_amdgcn_sched_barrier(0)
; template <class Epi>
; __device__ __forceinline__ void gemm_phase(LAS unsigned char* lds, const Gemm g, const StaticOrder& S, const Epi& E) {
;     ...
;             PG8_WAIT_V(8); PG8_WAIT_L(0); PG8_BAR; PG8_MMA(1, 0, At, B0); PG8_MMA(1, 1, At, B1); PG8_BAR; PG8_SCHED;
;             PG8_LDB(B0, 1, 0); PG8_LDB(B1, 1, 1); PG8_SCHED; PG8_LDA(At, 1, 0); PG8_STAGE(PG8_SA(0, 1), a2 + hstepA, voffA);
;             PG8_WAIT_V(8); PG8_WAIT_L(0); PG8_BAR; PG8_MMA(0, 0, At, B0); PG8_MMA(0, 1, At, B1); PG8_BAR; PG8_SCHED;
;             PG8_LDA(At, 1, 1); PG8_STAGE(PG8_SB(1, 0), b3, voffB); PG8_STAGE(PG8_SB(1, 1), b3 + hstepB, voffB); PG8_STAGE(PG8_SA(1, 0), a3, voffA);
;             PG8_WAIT_V(8); PG8_WAIT_L(0); PG8_BAR; PG8_MMA(1, 0, At, B0); PG8_MMA(1, 1, At, B1); PG8_BAR; PG8_SCHED;
	s_setprio 1
	s_waitcnt lgkmcnt(0)
	v_mfma_f32_16x16x32_bf16 v[62:65], v[130:133], v[176:179], v[62:65]
	v_mfma_f32_16x16x32_bf16 v[58:61], v[138:141], v[176:179], v[58:61]
	v_mfma_f32_16x16x32_bf16 v[50:53], v[130:133], v[192:195], v[50:53]
	v_mfma_f32_16x16x32_bf16 v[42:45], v[138:141], v[192:195], v[42:45]
	v_mfma_f32_16x16x32_bf16 v[30:33], v[130:133], v[200:203], v[30:33]
	v_mfma_f32_16x16x32_bf16 v[26:29], v[138:141], v[200:203], v[26:29]
	v_mfma_f32_16x16x32_bf16 v[18:21], v[130:133], v[208:211], v[18:21]
	v_mfma_f32_16x16x32_bf16 v[10:13], v[138:141], v[208:211], v[10:13]
	v_mfma_f32_16x16x32_bf16 v[62:65], v[134:137], v[188:191], v[62:65]
	v_mfma_f32_16x16x32_bf16 v[58:61], v[142:145], v[188:191], v[58:61]
	v_mfma_f32_16x16x32_bf16 v[50:53], v[134:137], v[196:199], v[50:53]
	v_mfma_f32_16x16x32_bf16 v[42:45], v[142:145], v[196:199], v[42:45]
	v_mfma_f32_16x16x32_bf16 v[30:33], v[134:137], v[204:207], v[30:33]
	v_mfma_f32_16x16x32_bf16 v[26:29], v[142:145], v[204:207], v[26:29]
	v_mfma_f32_16x16x32_bf16 v[18:21], v[134:137], v[212:215], v[18:21]
	v_mfma_f32_16x16x32_bf16 v[10:13], v[142:145], v[212:215], v[10:13]
	s_setprio 0
	s_setprio 1
	v_mfma_f32_16x16x32_bf16 v[54:57], v[146:149], v[176:179], v[54:57]
	v_mfma_f32_16x16x32_bf16 v[46:49], v[168:171], v[176:179], v[46:49]
	v_mfma_f32_16x16x32_bf16 v[38:41], v[146:149], v[192:195], v[38:41]
	v_mfma_f32_16x16x32_bf16 v[34:37], v[168:171], v[192:195], v[34:37]
	v_mfma_f32_16x16x32_bf16 v[22:25], v[146:149], v[200:203], v[22:25]
	v_mfma_f32_16x16x32_bf16 v[14:17], v[168:171], v[200:203], v[14:17]
	v_mfma_f32_16x16x32_bf16 v[6:9], v[146:149], v[208:211], v[6:9]
	v_mfma_f32_16x16x32_bf16 v[2:5], v[168:171], v[208:211], v[2:5]
	v_mfma_f32_16x16x32_bf16 v[54:57], v[162:165], v[188:191], v[54:57]
	v_mfma_f32_16x16x32_bf16 v[46:49], v[172:175], v[188:191], v[46:49]
	v_mfma_f32_16x16x32_bf16 v[38:41], v[162:165], v[196:199], v[38:41]
	v_mfma_f32_16x16x32_bf16 v[34:37], v[172:175], v[196:199], v[34:37]
	v_mfma_f32_16x16x32_bf16 v[22:25], v[162:165], v[204:207], v[22:25]
	v_mfma_f32_16x16x32_bf16 v[14:17], v[172:175], v[204:207], v[14:17]
	v_mfma_f32_16x16x32_bf16 v[6:9], v[162:165], v[212:215], v[6:9]
	v_mfma_f32_16x16x32_bf16 v[2:5], v[172:175], v[212:215], v[2:5]
	s_setprio 0
	s_barrier
	s_add_i32 s52, 0, 0x18000
	s_add_i32 s53, 0, 0x1c000
	v_add_u32_e32 v142, s52, v1
	v_add_u32_e32 v167, s53, v1
	ds_read_b128 v[130:133], v142
	ds_read_b128 v[134:137], v142 offset:1024
	ds_read_b128 v[138:141], v142 offset:2048
	ds_read_b128 v[142:145], v142 offset:3072
	ds_read_b128 v[146:149], v167
	ds_read_b128 v[162:165], v167 offset:1024
	ds_read_b128 v[168:171], v167 offset:2048
	ds_read_b128 v[172:175], v167 offset:3072
	s_add_u32 s26, s26, 0x200000
	s_addc_u32 s27, s27, 0
	s_mov_b32 m0, s35
	v_lshl_add_u64 v[222:223], s[26:27], 0, v[150:151]
	ds_read_b128 v[176:179], v166 offset:32768
	ds_read_b128 v[188:191], v166 offset:33792
	ds_read_b128 v[192:195], v166 offset:34816
	ds_read_b128 v[196:199], v166 offset:35840
	ds_read_b128 v[200:203], v166 offset:36864
	ds_read_b128 v[204:207], v166 offset:37888
	ds_read_b128 v[208:211], v166 offset:38912
	ds_read_b128 v[212:215], v166 offset:39936
	global_load_lds_dwordx4 v[222:223], off
	v_lshl_add_u64 v[222:223], s[26:27], 0, v[154:155]
	s_mov_b32 m0, s42
	s_nop 0
	global_load_lds_dwordx4 v[222:223], off
	s_waitcnt vmcnt(8)
	s_waitcnt lgkmcnt(0)
	s_barrier
	s_setprio 1
	s_waitcnt lgkmcnt(0)
	v_mfma_f32_16x16x32_bf16 v[126:129], v[130:133], v[176:179], v[126:129]
	v_mfma_f32_16x16x32_bf16 v[122:125], v[138:141], v[176:179], v[122:125]
	v_mfma_f32_16x16x32_bf16 v[118:121], v[130:133], v[192:195], v[118:121]
	v_mfma_f32_16x16x32_bf16 v[114:117], v[138:141], v[192:195], v[114:117]
	v_mfma_f32_16x16x32_bf16 v[94:97], v[130:133], v[200:203], v[94:97]
	v_mfma_f32_16x16x32_bf16 v[90:93], v[138:141], v[200:203], v[90:93]
	v_mfma_f32_16x16x32_bf16 v[82:85], v[130:133], v[208:211], v[82:85]
	v_mfma_f32_16x16x32_bf16 v[74:77], v[138:141], v[208:211], v[74:77]
	v_mfma_f32_16x16x32_bf16 v[126:129], v[134:137], v[188:191], v[126:129]
	v_mfma_f32_16x16x32_bf16 v[122:125], v[142:145], v[188:191], v[122:125]
	v_mfma_f32_16x16x32_bf16 v[118:121], v[134:137], v[196:199], v[118:121]
	v_mfma_f32_16x16x32_bf16 v[114:117], v[142:145], v[196:199], v[114:117]
	v_mfma_f32_16x16x32_bf16 v[94:97], v[134:137], v[204:207], v[94:97]
	v_mfma_f32_16x16x32_bf16 v[90:93], v[142:145], v[204:207], v[90:93]
	v_mfma_f32_16x16x32_bf16 v[82:85], v[134:137], v[212:215], v[82:85]
	v_mfma_f32_16x16x32_bf16 v[74:77], v[142:145], v[212:215], v[74:77]
	s_setprio 0
	s_setprio 1
	v_mfma_f32_16x16x32_bf16 v[110:113], v[146:149], v[176:179], v[110:113]
	v_mfma_f32_16x16x32_bf16 v[106:109], v[168:171], v[176:179], v[106:109]
	v_mfma_f32_16x16x32_bf16 v[102:105], v[146:149], v[192:195], v[102:105]
	v_mfma_f32_16x16x32_bf16 v[98:101], v[168:171], v[192:195], v[98:101]
	v_mfma_f32_16x16x32_bf16 v[86:89], v[146:149], v[200:203], v[86:89]
	v_mfma_f32_16x16x32_bf16 v[78:81], v[168:171], v[200:203], v[78:81]
	v_mfma_f32_16x16x32_bf16 v[70:73], v[146:149], v[208:211], v[70:73]
	v_mfma_f32_16x16x32_bf16 v[66:69], v[168:171], v[208:211], v[66:69]
	v_mfma_f32_16x16x32_bf16 v[110:113], v[162:165], v[188:191], v[110:113]
	v_mfma_f32_16x16x32_bf16 v[106:109], v[172:175], v[188:191], v[106:109]
	v_mfma_f32_16x16x32_bf16 v[102:105], v[162:165], v[196:199], v[102:105]
	v_mfma_f32_16x16x32_bf16 v[98:101], v[172:175], v[196:199], v[98:101]
	v_mfma_f32_16x16x32_bf16 v[86:89], v[162:165], v[204:207], v[86:89]
	v_mfma_f32_16x16x32_bf16 v[78:81], v[172:175], v[204:207], v[78:81]
	v_mfma_f32_16x16x32_bf16 v[70:73], v[162:165], v[212:215], v[70:73]
	v_mfma_f32_16x16x32_bf16 v[66:69], v[172:175], v[212:215], v[66:69]
	s_setprio 0
	s_barrier
; #define PG8_STAGE(bufoff, gbase, voff) do { _Pragma("unroll") for (int _i = 0; _i < 2; ++_i) \
;         __builtin_amdgcn_global_load_lds((const unsigned*)((const char*)(gbase) + (voff)[_i]), (LAS unsigned*)(lds + (bufoff) + ldsw + _i * 8192), 16, 0, 0); } while (0)
; #define PG8_LDA(dst, b, h) do { _Pragma("unroll") for (int m = 0; m < 4; ++m) _Pragma("unroll") for (int k = 0; k < 2; ++k) dst[m][k] = *(const LAS bf16x8*)(lds + PG8_SA(b, h) + aoff + m * 2048 + k * 1024); } while (0)
; #define PG8_MMA(ai, bj, At, Bt) do { __builtin_amdgcn_s_setprio(1); _Pragma("unroll") for (int m = 0; m < 4; ++m) _Pragma("unroll") for (int n = 0; n < 2; ++n) _Pragma("unroll") for (int k = 0; k < 2; ++k) \
;         acc[ai][bj][m][n] = __builtin_amdgcn_mfma_f32_16x16x32_bf16(Bt[n][k], At[m][k], acc[ai][bj][m][n], 0, 0, 0); __builtin_amdgcn_s_setprio(0); } while (0)
; #define PG8_WAIT_V(n) asm volatile("s_waitcnt vmcnt(" #n ")" ::: "memory")
; #define PG8_WAIT_L(n) asm volatile("s_waitcnt lgkmcnt(" #n ")" ::: "memory")
; #define PG8_BAR __builtin_amdgcn_s_barrier()
; #define PG8_SCHED __builtin_amdgcn_sched_barrier(0)
; template <class Epi>
; __device__ __forceinline__ void gemm_phase(LAS unsigned char* lds, const Gemm g, const StaticOrder& S, const Epi& E) {
;     ...
;             PG8_LDA(At, 1, 1); PG8_STAGE(PG8_SB(1, 0), b3, voffB); PG8_STAGE(PG8_SB(1, 1), b3 + hstepB, voffB); PG8_STAGE(PG8_SA(1, 0), a3, voffA);
;             PG8_WAIT_V(8); PG8_WAIT_L(0); PG8_BAR; PG8_MMA(1, 0, At, B0); PG8_MMA(1, 1, At, B1); PG8_BAR; PG8_SCHED;
;         }
;         if (wr == 0) PG8_BAR;
	s_add_i32 s26, s52, s30
	v_lshl_add_u64 v[184:185], v[184:185], 0, s[84:85]
	s_mov_b32 m0, s26
	ds_read_b128 v[176:179], v166 offset:49152
	ds_read_b128 v[188:191], v166 offset:50176
	ds_read_b128 v[192:195], v166 offset:51200
	ds_read_b128 v[196:199], v166 offset:52224
	ds_read_b128 v[200:203], v166 offset:53248
	ds_read_b128 v[204:207], v166 offset:54272
	ds_read_b128 v[208:211], v166 offset:55296
	ds_read_b128 v[212:215], v166 offset:56320
	global_load_lds_dwordx4 v[184:185], off
	s_add_i32 m0, s26, 0x2000
	s_add_u32 s14, s14, 0x200080
	v_lshl_add_u64 v[184:185], v[216:217], 0, s[84:85]
	s_addc_u32 s15, s15, 0
	s_add_i32 s26, s53, s30
	global_load_lds_dwordx4 v[184:185], off
	v_lshl_add_u64 v[184:185], s[14:15], 0, v[152:153]
	s_mov_b32 m0, s26
	s_nop 0
	global_load_lds_dwordx4 v[184:185], off
	v_lshl_add_u64 v[184:185], s[14:15], 0, v[156:157]
	s_add_i32 m0, s26, 0x2000
	s_nop 0
	global_load_lds_dwordx4 v[184:185], off
	v_lshl_add_u64 v[184:185], v[218:219], 0, s[84:85]
	s_mov_b32 m0, s68
	s_nop 0
	global_load_lds_dwordx4 v[184:185], off
	v_lshl_add_u64 v[184:185], v[220:221], 0, s[84:85]
	s_mov_b32 m0, s69
	s_nop 0
	global_load_lds_dwordx4 v[184:185], off
	s_waitcnt vmcnt(8)
	s_waitcnt lgkmcnt(0)
	s_barrier
	s_setprio 1
	s_waitcnt lgkmcnt(0)
	v_mfma_f32_16x16x32_bf16 v[62:65], v[130:133], v[176:179], v[62:65]
	v_mfma_f32_16x16x32_bf16 v[58:61], v[138:141], v[176:179], v[58:61]
	v_mfma_f32_16x16x32_bf16 v[50:53], v[130:133], v[192:195], v[50:53]
	v_mfma_f32_16x16x32_bf16 v[42:45], v[138:141], v[192:195], v[42:45]
	v_mfma_f32_16x16x32_bf16 v[30:33], v[130:133], v[200:203], v[30:33]
	v_mfma_f32_16x16x32_bf16 v[26:29], v[138:141], v[200:203], v[26:29]
	v_mfma_f32_16x16x32_bf16 v[18:21], v[130:133], v[208:211], v[18:21]
	v_mfma_f32_16x16x32_bf16 v[10:13], v[138:141], v[208:211], v[10:13]
	v_mfma_f32_16x16x32_bf16 v[62:65], v[134:137], v[188:191], v[62:65]
	v_mfma_f32_16x16x32_bf16 v[58:61], v[142:145], v[188:191], v[58:61]
	v_mfma_f32_16x16x32_bf16 v[50:53], v[134:137], v[196:199], v[50:53]
	v_mfma_f32_16x16x32_bf16 v[42:45], v[142:145], v[196:199], v[42:45]
	v_mfma_f32_16x16x32_bf16 v[30:33], v[134:137], v[204:207], v[30:33]
	v_mfma_f32_16x16x32_bf16 v[26:29], v[142:145], v[204:207], v[26:29]
	v_mfma_f32_16x16x32_bf16 v[18:21], v[134:137], v[212:215], v[18:21]
	v_mfma_f32_16x16x32_bf16 v[10:13], v[142:145], v[212:215], v[10:13]
	s_setprio 0
	s_setprio 1
	v_mfma_f32_16x16x32_bf16 v[54:57], v[146:149], v[176:179], v[54:57]
	v_mfma_f32_16x16x32_bf16 v[46:49], v[168:171], v[176:179], v[46:49]
	v_mfma_f32_16x16x32_bf16 v[38:41], v[146:149], v[192:195], v[38:41]
	v_mfma_f32_16x16x32_bf16 v[34:37], v[168:171], v[192:195], v[34:37]
	v_mfma_f32_16x16x32_bf16 v[22:25], v[146:149], v[200:203], v[22:25]
	v_mfma_f32_16x16x32_bf16 v[14:17], v[168:171], v[200:203], v[14:17]
	v_mfma_f32_16x16x32_bf16 v[6:9], v[146:149], v[208:211], v[6:9]
	v_mfma_f32_16x16x32_bf16 v[2:5], v[168:171], v[208:211], v[2:5]
	v_mfma_f32_16x16x32_bf16 v[54:57], v[162:165], v[188:191], v[54:57]
	v_mfma_f32_16x16x32_bf16 v[46:49], v[172:175], v[188:191], v[46:49]
	v_mfma_f32_16x16x32_bf16 v[38:41], v[162:165], v[196:199], v[38:41]
	v_mfma_f32_16x16x32_bf16 v[34:37], v[172:175], v[196:199], v[34:37]
	v_mfma_f32_16x16x32_bf16 v[22:25], v[162:165], v[204:207], v[22:25]
	v_mfma_f32_16x16x32_bf16 v[14:17], v[172:175], v[204:207], v[14:17]
	v_mfma_f32_16x16x32_bf16 v[6:9], v[162:165], v[212:215], v[6:9]
	v_mfma_f32_16x16x32_bf16 v[2:5], v[172:175], v[212:215], v[2:5]
	s_setprio 0
	s_barrier
	s_add_i32 s41, s41, 2
	s_add_u32 s24, s24, 0x100
	s_addc_u32 s25, s25, 0
	s_add_u32 s19, s19, 0x100
	s_addc_u32 s40, s40, 0
	s_cmpk_gt_u32 s41, 0x7d
	s_cbranch_scc0 .LBB0_2233
	s_cmp_ge_u32 s74, 16
	s_cbranch_scc1 .Lwpf_e
	s_lshl_b32 s100, s74, 9
	v_add_u32_e32 v130, s100, v246
	v_lshrrev_b32_e32 v131, 2, v130
	v_and_b32_e32 v130, 3, v130
	v_lshlrev_b32_e32 v130, 7, v130
	v_lshl_add_u32 v130, v131, 12, v130
	s_add_u32 s100, s88, 0x4000000
	s_addc_u32 s101, s89, 0
	s_mov_b32 m0, 0x21000
	s_nop 0
	global_load_lds_dword v130, s[100:101]
